# v31: + merged the two load-segment waits in the K-loops; SB partial sums start without add-0
# speedup vs baseline: 1.0106x; 1.0060x over previous
; #define PG8_STAGE(bufoff, gbase, voff) do { _Pragma("unroll") for (int _i = 0; _i < 2; ++_i) \
;         __builtin_amdgcn_global_load_lds((const unsigned*)((const char*)(gbase) + (voff)[_i]), (PG8_LAS unsigned*)(lds + (bufoff) + ldsw + _i * 8192), 16, 0, 0); } while (0)
; #define PG8_LDA(dst, b, h) do { _Pragma("unroll") for (int m = 0; m < 4; ++m) _Pragma("unroll") for (int k = 0; k < 2; ++k) dst[m][k] = *(const PG8_LAS bf16x8*)(lds + PG8_SA(b, h) + aoff + m * 2048 + k * 1024); } while (0)
; #define PG8_LDB(dst, b, h) do { _Pragma("unroll") for (int n = 0; n < 2; ++n) _Pragma("unroll") for (int k = 0; k < 2; ++k) dst[n][k] = *(const PG8_LAS bf16x8*)(lds + PG8_SB(b, h) + boff + n * 2048 + k * 1024); } while (0)
; #define PG8_MMA(ai, bj, At, Bt) do { __builtin_amdgcn_s_setprio(1); _Pragma("unroll") for (int m = 0; m < 4; ++m) _Pragma("unroll") for (int n = 0; n < 2; ++n) _Pragma("unroll") for (int k = 0; k < 2; ++k) \
;         acc[ai][bj][m][n] = __builtin_amdgcn_mfma_f32_16x16x32_bf16(Bt[n][k], At[m][k], acc[ai][bj][m][n], 0, 0, 0); __builtin_amdgcn_s_setprio(0); } while (0)
; #define PG8_WAIT_V(n) asm volatile("s_waitcnt vmcnt(" #n ")" ::: "memory")
; #define PG8_WAIT_L(n) asm volatile("s_waitcnt lgkmcnt(" #n ")" ::: "memory")
; #define PG8_BAR __builtin_amdgcn_s_barrier()
; template <class Epi, class Sched, bool ALIGN_EPI = false, bool SP2 = false>
; __device__ __forceinline__ void gemm_phase(PG8_LAS unsigned char* lds, const Gemm g, const Sched& S, const Epi& E, const int wave_s) {
;     ...
;         for (int t = 0; t < nt; t += 2) {
;             const bool last = (t == nt - 2);
;             const char* a1 = cA + (size_t)(t + 1) * kstep;
;             const char* a2 = last ? nA : cA + (size_t)(t + 2) * kstep; const char* b2 = last ? nB : cB + (size_t)(t + 2) * kstep;
;             const char* a3 = a2 + kstep; const char* b3 = b2 + kstep;
;             if (last && has_next) S.a_ready(nxt);
;             if constexpr (SP2) {
;             PG8_LDB(B0, 0, 0); PG8_LDB(B1, 0, 1); PG8_SCHED; PG8_LDA(At, 0, 0); PG8_STAGE(PG8_SA(1, 1), a1 + hstep, voffA);
;             PG8_WAIT_V(8); PG8_WAIT_L(0); PG8_BAR; PG8_MMA(0, 0, At, B0); PG8_MMA(0, 1, At, B1); PG8_BAR; PG8_SCHED;
;             PG8_LDA(At, 0, 1); PG8_STAGE(PG8_SB(0, 0), b2, voffB); PG8_STAGE(PG8_SB(0, 1), b2 + hstep, voffB); PG8_STAGE(PG8_SA(0, 0), a2, voffA);
.LBB0_219:
	s_add_u32 s34, s30, 0xfffc0080
	s_addc_u32 s35, s31, -1
	s_add_i32 s45, 0, 0x10000
	s_cmp_eq_u32 s68, 12
	s_cselect_b32 s37, s5, s35
	s_cselect_b32 s36, s23, s34
	v_add_u32_e32 v0, s45, v180
	s_cselect_b32 s35, s21, s64
	s_cselect_b32 s34, s29, s55
	s_add_i32 s75, 0, 0x14000
	ds_read_b128 v[78:81], v0
	ds_read_b128 v[86:89], v0 offset:1024
	ds_read_b128 v[98:101], v0 offset:2048
	ds_read_b128 v[102:105], v0 offset:3072
	v_add_u32_e32 v0, s75, v180
	ds_read_b128 v[170:173], v0
	ds_read_b128 v[174:177], v0 offset:1024
	ds_read_b128 v[184:187], v0 offset:2048
	ds_read_b128 v[188:191], v0 offset:3072
	v_lshl_add_u64 v[230:231], s[30:31], 0, v[164:165]
	s_add_i32 m0, s47, 0xc000
	ds_read_b128 v[192:195], v182
	ds_read_b128 v[196:199], v182 offset:1024
	ds_read_b128 v[200:203], v182 offset:2048
	ds_read_b128 v[210:213], v182 offset:3072
	ds_read_b128 v[214:217], v182 offset:4096
	ds_read_b128 v[218:221], v182 offset:5120
	ds_read_b128 v[222:225], v182 offset:6144
	ds_read_b128 v[226:229], v182 offset:7168
	global_load_lds_dwordx4 v[230:231], off
	v_lshl_add_u64 v[230:231], s[30:31], 0, v[166:167]
	s_add_i32 m0, s47, 0xe000
	s_nop 0
	global_load_lds_dwordx4 v[230:231], off
	s_waitcnt vmcnt(8) lgkmcnt(0)
	s_barrier
	s_setprio 1
	v_mfma_f32_16x16x32_bf16 v[142:145], v[78:81], v[192:195], v[142:145]
	v_mfma_f32_16x16x32_bf16 v[138:141], v[98:101], v[192:195], v[138:141]
	v_mfma_f32_16x16x32_bf16 v[126:129], v[78:81], v[200:203], v[126:129]
	v_mfma_f32_16x16x32_bf16 v[122:125], v[98:101], v[200:203], v[122:125]
	v_mfma_f32_16x16x32_bf16 v[110:113], v[78:81], v[214:217], v[110:113]
	v_mfma_f32_16x16x32_bf16 v[106:109], v[98:101], v[214:217], v[106:109]
	v_mfma_f32_16x16x32_bf16 v[82:85], v[78:81], v[222:225], v[82:85]
	v_mfma_f32_16x16x32_bf16 v[74:77], v[98:101], v[222:225], v[74:77]
	v_mfma_f32_16x16x32_bf16 v[142:145], v[86:89], v[196:199], v[142:145]
	v_mfma_f32_16x16x32_bf16 v[138:141], v[102:105], v[196:199], v[138:141]
	v_mfma_f32_16x16x32_bf16 v[126:129], v[86:89], v[210:213], v[126:129]
	v_mfma_f32_16x16x32_bf16 v[122:125], v[102:105], v[210:213], v[122:125]
	v_mfma_f32_16x16x32_bf16 v[110:113], v[86:89], v[218:221], v[110:113]
	v_mfma_f32_16x16x32_bf16 v[106:109], v[102:105], v[218:221], v[106:109]
	v_mfma_f32_16x16x32_bf16 v[82:85], v[86:89], v[226:229], v[82:85]
	v_mfma_f32_16x16x32_bf16 v[74:77], v[102:105], v[226:229], v[74:77]
	s_setprio 0
	s_setprio 1
	v_mfma_f32_16x16x32_bf16 v[134:137], v[170:173], v[192:195], v[134:137]
	v_mfma_f32_16x16x32_bf16 v[130:133], v[184:187], v[192:195], v[130:133]
	v_mfma_f32_16x16x32_bf16 v[118:121], v[170:173], v[200:203], v[118:121]
	v_mfma_f32_16x16x32_bf16 v[114:117], v[184:187], v[200:203], v[114:117]
	v_mfma_f32_16x16x32_bf16 v[94:97], v[170:173], v[214:217], v[94:97]
	v_mfma_f32_16x16x32_bf16 v[90:93], v[184:187], v[214:217], v[90:93]
	v_mfma_f32_16x16x32_bf16 v[70:73], v[170:173], v[222:225], v[70:73]
	v_mfma_f32_16x16x32_bf16 v[66:69], v[184:187], v[222:225], v[66:69]
	v_mfma_f32_16x16x32_bf16 v[134:137], v[174:177], v[196:199], v[134:137]
	v_mfma_f32_16x16x32_bf16 v[130:133], v[188:191], v[196:199], v[130:133]
	v_mfma_f32_16x16x32_bf16 v[118:121], v[174:177], v[210:213], v[118:121]
	v_mfma_f32_16x16x32_bf16 v[114:117], v[188:191], v[210:213], v[114:117]
	v_mfma_f32_16x16x32_bf16 v[94:97], v[174:177], v[218:221], v[94:97]
	v_mfma_f32_16x16x32_bf16 v[90:93], v[188:191], v[218:221], v[90:93]
	v_mfma_f32_16x16x32_bf16 v[70:73], v[174:177], v[226:229], v[70:73]
	v_mfma_f32_16x16x32_bf16 v[66:69], v[188:191], v[226:229], v[66:69]
	s_barrier
	s_setprio 0
	s_add_i32 s45, s45, s44
	v_lshl_add_u64 v[230:231], s[34:35], 0, v[148:149]
	s_mov_b32 m0, s45
	ds_read_b128 v[192:195], v182 offset:16384
	ds_read_b128 v[196:199], v182 offset:17408
	ds_read_b128 v[200:203], v182 offset:18432
	ds_read_b128 v[210:213], v182 offset:19456
	ds_read_b128 v[214:217], v182 offset:20480
	ds_read_b128 v[218:221], v182 offset:21504
	ds_read_b128 v[222:225], v182 offset:22528
	ds_read_b128 v[226:229], v182 offset:23552
	global_load_lds_dwordx4 v[230:231], off
	s_add_i32 m0, s45, 0x2000
	s_add_u32 s80, s34, 0x40000
	v_lshl_add_u64 v[232:233], s[34:35], 0, v[152:153]
	s_addc_u32 s81, s35, 0
	s_add_i32 s45, s75, s44
	global_load_lds_dwordx4 v[232:233], off
	v_lshl_add_u64 v[234:235], s[80:81], 0, v[148:149]
	s_mov_b32 m0, s45
	v_lshl_add_u64 v[236:237], s[36:37], 0, v[150:151]
	global_load_lds_dwordx4 v[234:235], off
	v_lshl_add_u64 v[234:235], s[80:81], 0, v[152:153]
	s_add_i32 m0, s45, 0x2000
	s_nop 0
	global_load_lds_dwordx4 v[234:235], off
	v_lshl_add_u64 v[234:235], s[36:37], 0, v[146:147]
	s_mov_b32 m0, s47
	s_nop 0
	global_load_lds_dwordx4 v[234:235], off
	s_mov_b32 m0, s48
	s_nop 0
	global_load_lds_dwordx4 v[236:237], off
	s_waitcnt vmcnt(8) lgkmcnt(0)
	s_barrier
; #define PG8_STAGE(bufoff, gbase, voff) do { _Pragma("unroll") for (int _i = 0; _i < 2; ++_i) \
;         __builtin_amdgcn_global_load_lds((const unsigned*)((const char*)(gbase) + (voff)[_i]), (PG8_LAS unsigned*)(lds + (bufoff) + ldsw + _i * 8192), 16, 0, 0); } while (0)
; #define PG8_LDA(dst, b, h) do { _Pragma("unroll") for (int m = 0; m < 4; ++m) _Pragma("unroll") for (int k = 0; k < 2; ++k) dst[m][k] = *(const PG8_LAS bf16x8*)(lds + PG8_SA(b, h) + aoff + m * 2048 + k * 1024); } while (0)
; #define PG8_LDB(dst, b, h) do { _Pragma("unroll") for (int n = 0; n < 2; ++n) _Pragma("unroll") for (int k = 0; k < 2; ++k) dst[n][k] = *(const PG8_LAS bf16x8*)(lds + PG8_SB(b, h) + boff + n * 2048 + k * 1024); } while (0)
; #define PG8_MMA(ai, bj, At, Bt) do { __builtin_amdgcn_s_setprio(1); _Pragma("unroll") for (int m = 0; m < 4; ++m) _Pragma("unroll") for (int n = 0; n < 2; ++n) _Pragma("unroll") for (int k = 0; k < 2; ++k) \
;         acc[ai][bj][m][n] = __builtin_amdgcn_mfma_f32_16x16x32_bf16(Bt[n][k], At[m][k], acc[ai][bj][m][n], 0, 0, 0); __builtin_amdgcn_s_setprio(0); } while (0)
; #define PG8_WAIT_V(n) asm volatile("s_waitcnt vmcnt(" #n ")" ::: "memory")
; #define PG8_WAIT_L(n) asm volatile("s_waitcnt lgkmcnt(" #n ")" ::: "memory")
; #define PG8_BAR __builtin_amdgcn_s_barrier()
; #define PG8_SCHED __builtin_amdgcn_sched_barrier(0)
; template <class Epi, class Sched, bool ALIGN_EPI = false, bool SP2 = false>
; __device__ __forceinline__ void gemm_phase(PG8_LAS unsigned char* lds, const Gemm g, const Sched& S, const Epi& E, const int wave_s) {
;     ...
;             PG8_WAIT_V(8); PG8_WAIT_L(0); PG8_BAR; PG8_MMA(1, 0, At, B0); PG8_MMA(1, 1, At, B1); PG8_BAR; PG8_SCHED;
;             PG8_LDB(B0, 1, 0); PG8_LDB(B1, 1, 1); PG8_SCHED; PG8_LDA(At, 1, 0); PG8_STAGE(PG8_SA(0, 1), a2 + hstep, voffA);
;             PG8_WAIT_V(8); PG8_WAIT_L(0); PG8_BAR; PG8_MMA(0, 0, At, B0); PG8_MMA(0, 1, At, B1); PG8_BAR; PG8_SCHED;
	s_setprio 1
	v_mfma_f32_16x16x32_bf16 v[62:65], v[78:81], v[192:195], v[62:65]
	v_mfma_f32_16x16x32_bf16 v[58:61], v[98:101], v[192:195], v[58:61]
	v_mfma_f32_16x16x32_bf16 v[46:49], v[78:81], v[200:203], v[46:49]
	v_mfma_f32_16x16x32_bf16 v[42:45], v[98:101], v[200:203], v[42:45]
	v_mfma_f32_16x16x32_bf16 v[30:33], v[78:81], v[214:217], v[30:33]
	v_mfma_f32_16x16x32_bf16 v[26:29], v[98:101], v[214:217], v[26:29]
	v_mfma_f32_16x16x32_bf16 v[14:17], v[78:81], v[222:225], v[14:17]
	v_mfma_f32_16x16x32_bf16 v[10:13], v[98:101], v[222:225], v[10:13]
	v_mfma_f32_16x16x32_bf16 v[62:65], v[86:89], v[196:199], v[62:65]
	v_mfma_f32_16x16x32_bf16 v[58:61], v[102:105], v[196:199], v[58:61]
	v_mfma_f32_16x16x32_bf16 v[46:49], v[86:89], v[210:213], v[46:49]
	v_mfma_f32_16x16x32_bf16 v[42:45], v[102:105], v[210:213], v[42:45]
	v_mfma_f32_16x16x32_bf16 v[30:33], v[86:89], v[218:221], v[30:33]
	v_mfma_f32_16x16x32_bf16 v[26:29], v[102:105], v[218:221], v[26:29]
	v_mfma_f32_16x16x32_bf16 v[14:17], v[86:89], v[226:229], v[14:17]
	v_mfma_f32_16x16x32_bf16 v[10:13], v[102:105], v[226:229], v[10:13]
	s_setprio 0
	s_setprio 1
	v_mfma_f32_16x16x32_bf16 v[54:57], v[170:173], v[192:195], v[54:57]
	v_mfma_f32_16x16x32_bf16 v[50:53], v[184:187], v[192:195], v[50:53]
	v_mfma_f32_16x16x32_bf16 v[38:41], v[170:173], v[200:203], v[38:41]
	v_mfma_f32_16x16x32_bf16 v[34:37], v[184:187], v[200:203], v[34:37]
	v_mfma_f32_16x16x32_bf16 v[22:25], v[170:173], v[214:217], v[22:25]
	v_mfma_f32_16x16x32_bf16 v[18:21], v[184:187], v[214:217], v[18:21]
	v_mfma_f32_16x16x32_bf16 v[6:9], v[170:173], v[222:225], v[6:9]
	v_mfma_f32_16x16x32_bf16 v[2:5], v[184:187], v[222:225], v[2:5]
	v_mfma_f32_16x16x32_bf16 v[54:57], v[174:177], v[196:199], v[54:57]
	v_mfma_f32_16x16x32_bf16 v[50:53], v[188:191], v[196:199], v[50:53]
	v_mfma_f32_16x16x32_bf16 v[38:41], v[174:177], v[210:213], v[38:41]
	v_mfma_f32_16x16x32_bf16 v[34:37], v[188:191], v[210:213], v[34:37]
	v_mfma_f32_16x16x32_bf16 v[22:25], v[174:177], v[218:221], v[22:25]
	v_mfma_f32_16x16x32_bf16 v[18:21], v[188:191], v[218:221], v[18:21]
	v_mfma_f32_16x16x32_bf16 v[6:9], v[174:177], v[226:229], v[6:9]
	v_mfma_f32_16x16x32_bf16 v[2:5], v[188:191], v[226:229], v[2:5]
	s_barrier
	s_setprio 0
	s_add_i32 s45, 0, 0x18000
	v_add_u32_e32 v0, s45, v180
	s_add_i32 s75, 0, 0x1c000
	ds_read_b128 v[78:81], v0
	ds_read_b128 v[86:89], v0 offset:1024
	ds_read_b128 v[98:101], v0 offset:2048
	ds_read_b128 v[102:105], v0 offset:3072
	v_add_u32_e32 v0, s75, v180
	ds_read_b128 v[170:173], v0
	ds_read_b128 v[174:177], v0 offset:1024
	ds_read_b128 v[184:187], v0 offset:2048
	ds_read_b128 v[188:191], v0 offset:3072
	s_add_u32 s36, s36, 0x40000
	s_addc_u32 s37, s37, 0
	s_mov_b32 m0, s49
	v_lshl_add_u64 v[238:239], s[36:37], 0, v[146:147]
	ds_read_b128 v[192:195], v182 offset:32768
	ds_read_b128 v[196:199], v182 offset:33792
	ds_read_b128 v[200:203], v182 offset:34816
	ds_read_b128 v[210:213], v182 offset:35840
	ds_read_b128 v[214:217], v182 offset:36864
	ds_read_b128 v[218:221], v182 offset:37888
	ds_read_b128 v[222:225], v182 offset:38912
	ds_read_b128 v[226:229], v182 offset:39936
	global_load_lds_dwordx4 v[238:239], off
	v_lshl_add_u64 v[238:239], s[36:37], 0, v[150:151]
	s_mov_b32 m0, s50
	s_nop 0
	global_load_lds_dwordx4 v[238:239], off
	s_waitcnt vmcnt(8) lgkmcnt(0)
	s_barrier
	s_setprio 1
	v_mfma_f32_16x16x32_bf16 v[142:145], v[78:81], v[192:195], v[142:145]
	v_mfma_f32_16x16x32_bf16 v[138:141], v[98:101], v[192:195], v[138:141]
	v_mfma_f32_16x16x32_bf16 v[126:129], v[78:81], v[200:203], v[126:129]
	v_mfma_f32_16x16x32_bf16 v[122:125], v[98:101], v[200:203], v[122:125]
	v_mfma_f32_16x16x32_bf16 v[110:113], v[78:81], v[214:217], v[110:113]
	v_mfma_f32_16x16x32_bf16 v[106:109], v[98:101], v[214:217], v[106:109]
	v_mfma_f32_16x16x32_bf16 v[82:85], v[78:81], v[222:225], v[82:85]
	v_mfma_f32_16x16x32_bf16 v[74:77], v[98:101], v[222:225], v[74:77]
	v_mfma_f32_16x16x32_bf16 v[142:145], v[86:89], v[196:199], v[142:145]
	v_mfma_f32_16x16x32_bf16 v[138:141], v[102:105], v[196:199], v[138:141]
	v_mfma_f32_16x16x32_bf16 v[126:129], v[86:89], v[210:213], v[126:129]
	v_mfma_f32_16x16x32_bf16 v[122:125], v[102:105], v[210:213], v[122:125]
	v_mfma_f32_16x16x32_bf16 v[110:113], v[86:89], v[218:221], v[110:113]
	v_mfma_f32_16x16x32_bf16 v[106:109], v[102:105], v[218:221], v[106:109]
	v_mfma_f32_16x16x32_bf16 v[82:85], v[86:89], v[226:229], v[82:85]
	v_mfma_f32_16x16x32_bf16 v[74:77], v[102:105], v[226:229], v[74:77]
	s_setprio 0
	s_setprio 1
	v_mfma_f32_16x16x32_bf16 v[134:137], v[170:173], v[192:195], v[134:137]
	v_mfma_f32_16x16x32_bf16 v[130:133], v[184:187], v[192:195], v[130:133]
	v_mfma_f32_16x16x32_bf16 v[118:121], v[170:173], v[200:203], v[118:121]
	v_mfma_f32_16x16x32_bf16 v[114:117], v[184:187], v[200:203], v[114:117]
	v_mfma_f32_16x16x32_bf16 v[94:97], v[170:173], v[214:217], v[94:97]
	v_mfma_f32_16x16x32_bf16 v[90:93], v[184:187], v[214:217], v[90:93]
	v_mfma_f32_16x16x32_bf16 v[70:73], v[170:173], v[222:225], v[70:73]
	v_mfma_f32_16x16x32_bf16 v[66:69], v[184:187], v[222:225], v[66:69]
	v_mfma_f32_16x16x32_bf16 v[134:137], v[174:177], v[196:199], v[134:137]
	v_mfma_f32_16x16x32_bf16 v[130:133], v[188:191], v[196:199], v[130:133]
	v_mfma_f32_16x16x32_bf16 v[118:121], v[174:177], v[210:213], v[118:121]
	v_mfma_f32_16x16x32_bf16 v[114:117], v[188:191], v[210:213], v[114:117]
	v_mfma_f32_16x16x32_bf16 v[94:97], v[174:177], v[218:221], v[94:97]
	v_mfma_f32_16x16x32_bf16 v[90:93], v[188:191], v[218:221], v[90:93]
	v_mfma_f32_16x16x32_bf16 v[70:73], v[174:177], v[226:229], v[70:73]
	v_mfma_f32_16x16x32_bf16 v[66:69], v[188:191], v[226:229], v[66:69]
	s_barrier
; #define PG8_STAGE(bufoff, gbase, voff) do { _Pragma("unroll") for (int _i = 0; _i < 2; ++_i) \
;         __builtin_amdgcn_global_load_lds((const unsigned*)((const char*)(gbase) + (voff)[_i]), (PG8_LAS unsigned*)(lds + (bufoff) + ldsw + _i * 8192), 16, 0, 0); } while (0)
; #define PG8_LDA(dst, b, h) do { _Pragma("unroll") for (int m = 0; m < 4; ++m) _Pragma("unroll") for (int k = 0; k < 2; ++k) dst[m][k] = *(const PG8_LAS bf16x8*)(lds + PG8_SA(b, h) + aoff + m * 2048 + k * 1024); } while (0)
; #define PG8_MMA(ai, bj, At, Bt) do { __builtin_amdgcn_s_setprio(1); _Pragma("unroll") for (int m = 0; m < 4; ++m) _Pragma("unroll") for (int n = 0; n < 2; ++n) _Pragma("unroll") for (int k = 0; k < 2; ++k) \
;         acc[ai][bj][m][n] = __builtin_amdgcn_mfma_f32_16x16x32_bf16(Bt[n][k], At[m][k], acc[ai][bj][m][n], 0, 0, 0); __builtin_amdgcn_s_setprio(0); } while (0)
; #define PG8_WAIT_V(n) asm volatile("s_waitcnt vmcnt(" #n ")" ::: "memory")
; #define PG8_WAIT_L(n) asm volatile("s_waitcnt lgkmcnt(" #n ")" ::: "memory")
; #define PG8_BAR __builtin_amdgcn_s_barrier()
; #define PG8_SCHED __builtin_amdgcn_sched_barrier(0)
; template <class Epi, class Sched, bool ALIGN_EPI = false, bool SP2 = false>
; __device__ __forceinline__ void gemm_phase(PG8_LAS unsigned char* lds, const Gemm g, const Sched& S, const Epi& E, const int wave_s) {
;     ...
;             PG8_LDA(At, 1, 1); PG8_STAGE(PG8_SB(1, 0), b3, voffB); PG8_STAGE(PG8_SB(1, 1), b3 + hstep, voffB); PG8_STAGE(PG8_SA(1, 0), a3, voffA);
;             PG8_WAIT_V(8); PG8_WAIT_L(0); PG8_BAR; PG8_MMA(1, 0, At, B0); PG8_MMA(1, 1, At, B1); PG8_BAR; PG8_SCHED;
;     ...
;         if constexpr (ALIGN_EPI) { if (wr == 0) PG8_BAR; }
	s_setprio 0
	s_add_i32 s36, s45, s44
	v_lshl_add_u64 v[230:231], v[230:231], 0, s[70:71]
	s_mov_b32 m0, s36
	ds_read_b128 v[192:195], v182 offset:49152
	ds_read_b128 v[196:199], v182 offset:50176
	ds_read_b128 v[200:203], v182 offset:51200
	ds_read_b128 v[210:213], v182 offset:52224
	ds_read_b128 v[214:217], v182 offset:53248
	ds_read_b128 v[218:221], v182 offset:54272
	ds_read_b128 v[222:225], v182 offset:55296
	ds_read_b128 v[226:229], v182 offset:56320
	global_load_lds_dwordx4 v[230:231], off
	s_add_i32 m0, s36, 0x2000
	s_add_u32 s34, s34, 0x40080
	v_lshl_add_u64 v[230:231], v[232:233], 0, s[70:71]
	s_addc_u32 s35, s35, 0
	s_add_i32 s36, s75, s44
	global_load_lds_dwordx4 v[230:231], off
	v_lshl_add_u64 v[230:231], s[34:35], 0, v[148:149]
	s_mov_b32 m0, s36
	s_nop 0
	global_load_lds_dwordx4 v[230:231], off
	v_lshl_add_u64 v[230:231], s[34:35], 0, v[152:153]
	s_add_i32 m0, s36, 0x2000
	s_nop 0
	global_load_lds_dwordx4 v[230:231], off
	v_lshl_add_u64 v[230:231], v[234:235], 0, s[70:71]
	s_mov_b32 m0, s58
	s_nop 0
	global_load_lds_dwordx4 v[230:231], off
	v_lshl_add_u64 v[230:231], v[236:237], 0, s[70:71]
	s_mov_b32 m0, s59
	s_nop 0
	global_load_lds_dwordx4 v[230:231], off
	s_waitcnt vmcnt(8) lgkmcnt(0)
	s_barrier
	s_setprio 1
	v_mfma_f32_16x16x32_bf16 v[62:65], v[78:81], v[192:195], v[62:65]
	v_mfma_f32_16x16x32_bf16 v[58:61], v[98:101], v[192:195], v[58:61]
	v_mfma_f32_16x16x32_bf16 v[46:49], v[78:81], v[200:203], v[46:49]
	v_mfma_f32_16x16x32_bf16 v[42:45], v[98:101], v[200:203], v[42:45]
	v_mfma_f32_16x16x32_bf16 v[30:33], v[78:81], v[214:217], v[30:33]
	v_mfma_f32_16x16x32_bf16 v[26:29], v[98:101], v[214:217], v[26:29]
	v_mfma_f32_16x16x32_bf16 v[14:17], v[78:81], v[222:225], v[14:17]
	v_mfma_f32_16x16x32_bf16 v[10:13], v[98:101], v[222:225], v[10:13]
	v_mfma_f32_16x16x32_bf16 v[62:65], v[86:89], v[196:199], v[62:65]
	v_mfma_f32_16x16x32_bf16 v[58:61], v[102:105], v[196:199], v[58:61]
	v_mfma_f32_16x16x32_bf16 v[46:49], v[86:89], v[210:213], v[46:49]
	v_mfma_f32_16x16x32_bf16 v[42:45], v[102:105], v[210:213], v[42:45]
	v_mfma_f32_16x16x32_bf16 v[30:33], v[86:89], v[218:221], v[30:33]
	v_mfma_f32_16x16x32_bf16 v[26:29], v[102:105], v[218:221], v[26:29]
	v_mfma_f32_16x16x32_bf16 v[14:17], v[86:89], v[226:229], v[14:17]
	v_mfma_f32_16x16x32_bf16 v[10:13], v[102:105], v[226:229], v[10:13]
	s_setprio 0
	s_setprio 1
	v_mfma_f32_16x16x32_bf16 v[54:57], v[170:173], v[192:195], v[54:57]
	v_mfma_f32_16x16x32_bf16 v[50:53], v[184:187], v[192:195], v[50:53]
	v_mfma_f32_16x16x32_bf16 v[38:41], v[170:173], v[200:203], v[38:41]
	v_mfma_f32_16x16x32_bf16 v[34:37], v[184:187], v[200:203], v[34:37]
	v_mfma_f32_16x16x32_bf16 v[22:25], v[170:173], v[214:217], v[22:25]
	v_mfma_f32_16x16x32_bf16 v[18:21], v[184:187], v[214:217], v[18:21]
	v_mfma_f32_16x16x32_bf16 v[6:9], v[170:173], v[222:225], v[6:9]
	v_mfma_f32_16x16x32_bf16 v[2:5], v[184:187], v[222:225], v[2:5]
	v_mfma_f32_16x16x32_bf16 v[54:57], v[174:177], v[196:199], v[54:57]
	v_mfma_f32_16x16x32_bf16 v[50:53], v[188:191], v[196:199], v[50:53]
	v_mfma_f32_16x16x32_bf16 v[38:41], v[174:177], v[210:213], v[38:41]
	v_mfma_f32_16x16x32_bf16 v[34:37], v[188:191], v[210:213], v[34:37]
	v_mfma_f32_16x16x32_bf16 v[22:25], v[174:177], v[218:221], v[22:25]
	v_mfma_f32_16x16x32_bf16 v[18:21], v[188:191], v[218:221], v[18:21]
	v_mfma_f32_16x16x32_bf16 v[6:9], v[174:177], v[226:229], v[6:9]
	v_mfma_f32_16x16x32_bf16 v[2:5], v[188:191], v[226:229], v[2:5]
	s_barrier
	s_setprio 0
	s_add_i32 s68, s68, 2
	s_add_u32 s30, s30, 0x100
	s_addc_u32 s31, s31, 0
	s_add_u32 s55, s55, 0x100
	s_addc_u32 s64, s64, 0
	s_cmp_gt_u32 s68, 13
	s_cbranch_scc0 .LBB0_219
	s_and_b64 vcc, exec, s[18:19]
	s_cbranch_vccz .LBB0_222
	s_barrier

; #define PG8_STAGE(bufoff, gbase, voff) do { _Pragma("unroll") for (int _i = 0; _i < 2; ++_i) \
;         __builtin_amdgcn_global_load_lds((const unsigned*)((const char*)(gbase) + (voff)[_i]), (PG8_LAS unsigned*)(lds + (bufoff) + ldsw + _i * 8192), 16, 0, 0); } while (0)
; #define PG8_LDA(dst, b, h) do { _Pragma("unroll") for (int m = 0; m < 4; ++m) _Pragma("unroll") for (int k = 0; k < 2; ++k) dst[m][k] = *(const PG8_LAS bf16x8*)(lds + PG8_SA(b, h) + aoff + m * 2048 + k * 1024); } while (0)
; #define PG8_LDB(dst, b, h) do { _Pragma("unroll") for (int n = 0; n < 2; ++n) _Pragma("unroll") for (int k = 0; k < 2; ++k) dst[n][k] = *(const PG8_LAS bf16x8*)(lds + PG8_SB(b, h) + boff + n * 2048 + k * 1024); } while (0)
; #define PG8_MMA(ai, bj, At, Bt) do { __builtin_amdgcn_s_setprio(1); _Pragma("unroll") for (int m = 0; m < 4; ++m) _Pragma("unroll") for (int n = 0; n < 2; ++n) _Pragma("unroll") for (int k = 0; k < 2; ++k) \
;         acc[ai][bj][m][n] = __builtin_amdgcn_mfma_f32_16x16x32_bf16(Bt[n][k], At[m][k], acc[ai][bj][m][n], 0, 0, 0); __builtin_amdgcn_s_setprio(0); } while (0)
; #define PG8_WAIT_V(n) asm volatile("s_waitcnt vmcnt(" #n ")" ::: "memory")
; #define PG8_WAIT_L(n) asm volatile("s_waitcnt lgkmcnt(" #n ")" ::: "memory")
; #define PG8_BAR __builtin_amdgcn_s_barrier()
; template <class Epi, class Sched, bool ALIGN_EPI = false, bool SP2 = false>
; __device__ __forceinline__ void gemm_phase(PG8_LAS unsigned char* lds, const Gemm g, const Sched& S, const Epi& E, const int wave_s) {
;     ...
;         for (int t = 0; t < nt; t += 2) {
;             const bool last = (t == nt - 2);
;             const char* a1 = cA + (size_t)(t + 1) * kstep;
;             const char* a2 = last ? nA : cA + (size_t)(t + 2) * kstep; const char* b2 = last ? nB : cB + (size_t)(t + 2) * kstep;
;             const char* a3 = a2 + kstep; const char* b3 = b2 + kstep;
;             if (last && has_next) S.a_ready(nxt);
;             if constexpr (SP2) {
;             PG8_LDB(B0, 0, 0); PG8_LDB(B1, 0, 1); PG8_SCHED; PG8_LDA(At, 0, 0); PG8_STAGE(PG8_SA(1, 1), a1 + hstep, voffA);
;             PG8_WAIT_V(8); PG8_WAIT_L(0); PG8_BAR; PG8_MMA(0, 0, At, B0); PG8_MMA(0, 1, At, B1); PG8_BAR; PG8_SCHED;
;             PG8_LDA(At, 0, 1); PG8_STAGE(PG8_SB(0, 0), b2, voffB); PG8_STAGE(PG8_SB(0, 1), b2 + hstep, voffB); PG8_STAGE(PG8_SA(0, 0), a2, voffA);
.LBB0_325:
	s_add_u32 s30, s28, 0xfffc0080
	s_addc_u32 s31, s29, -1
	s_add_i32 s45, 0, 0x10000
	s_cmp_eq_u32 s68, 12
	s_cselect_b32 s35, s19, s31
	s_cselect_b32 s34, s25, s30
	v_add_u32_e32 v0, s45, v181
	s_cselect_b32 s31, s17, s65
	s_cselect_b32 s30, s55, s64
	s_add_i32 s75, 0, 0x14000
	ds_read_b128 v[130:133], v0
	ds_read_b128 v[134:137], v0 offset:1024
	ds_read_b128 v[138:141], v0 offset:2048
	ds_read_b128 v[142:145], v0 offset:3072
	v_add_u32_e32 v0, s75, v181
	ds_read_b128 v[172:175], v0
	ds_read_b128 v[176:179], v0 offset:1024
	ds_read_b128 v[186:189], v0 offset:2048
	ds_read_b128 v[190:193], v0 offset:3072
	v_lshl_add_u64 v[202:203], s[28:29], 0, v[168:169]
	s_add_i32 m0, s27, 0xc000
	ds_read_b128 v[194:197], v185
	ds_read_b128 v[198:201], v185 offset:1024
	ds_read_b128 v[210:213], v185 offset:2048
	ds_read_b128 v[214:217], v185 offset:3072
	ds_read_b128 v[218:221], v185 offset:4096
	ds_read_b128 v[222:225], v185 offset:5120
	ds_read_b128 v[226:229], v185 offset:6144
	ds_read_b128 v[230:233], v185 offset:7168
	global_load_lds_dwordx4 v[202:203], off
	v_lshl_add_u64 v[202:203], s[28:29], 0, v[170:171]
	s_add_i32 m0, s27, 0xe000
	s_nop 0
	global_load_lds_dwordx4 v[202:203], off
	s_waitcnt vmcnt(8) lgkmcnt(0)
	s_barrier
	s_setprio 1
	v_mfma_f32_16x16x32_bf16 v[126:129], v[130:133], v[194:197], v[126:129]
	v_mfma_f32_16x16x32_bf16 v[122:125], v[138:141], v[194:197], v[122:125]
	v_mfma_f32_16x16x32_bf16 v[110:113], v[130:133], v[210:213], v[110:113]
	v_mfma_f32_16x16x32_bf16 v[106:109], v[138:141], v[210:213], v[106:109]
	v_mfma_f32_16x16x32_bf16 v[94:97], v[130:133], v[218:221], v[94:97]
	v_mfma_f32_16x16x32_bf16 v[90:93], v[138:141], v[218:221], v[90:93]
	v_mfma_f32_16x16x32_bf16 v[78:81], v[130:133], v[226:229], v[78:81]
	v_mfma_f32_16x16x32_bf16 v[74:77], v[138:141], v[226:229], v[74:77]
	v_mfma_f32_16x16x32_bf16 v[126:129], v[134:137], v[198:201], v[126:129]
	v_mfma_f32_16x16x32_bf16 v[122:125], v[142:145], v[198:201], v[122:125]
	v_mfma_f32_16x16x32_bf16 v[110:113], v[134:137], v[214:217], v[110:113]
	v_mfma_f32_16x16x32_bf16 v[106:109], v[142:145], v[214:217], v[106:109]
	v_mfma_f32_16x16x32_bf16 v[94:97], v[134:137], v[222:225], v[94:97]
	v_mfma_f32_16x16x32_bf16 v[90:93], v[142:145], v[222:225], v[90:93]
	v_mfma_f32_16x16x32_bf16 v[78:81], v[134:137], v[230:233], v[78:81]
	v_mfma_f32_16x16x32_bf16 v[74:77], v[142:145], v[230:233], v[74:77]
	s_setprio 0
	s_setprio 1
	v_mfma_f32_16x16x32_bf16 v[118:121], v[172:175], v[194:197], v[118:121]
	v_mfma_f32_16x16x32_bf16 v[114:117], v[186:189], v[194:197], v[114:117]
	v_mfma_f32_16x16x32_bf16 v[102:105], v[172:175], v[210:213], v[102:105]
	v_mfma_f32_16x16x32_bf16 v[98:101], v[186:189], v[210:213], v[98:101]
	v_mfma_f32_16x16x32_bf16 v[86:89], v[172:175], v[218:221], v[86:89]
	v_mfma_f32_16x16x32_bf16 v[82:85], v[186:189], v[218:221], v[82:85]
	v_mfma_f32_16x16x32_bf16 v[70:73], v[172:175], v[226:229], v[70:73]
	v_mfma_f32_16x16x32_bf16 v[66:69], v[186:189], v[226:229], v[66:69]
	v_mfma_f32_16x16x32_bf16 v[118:121], v[176:179], v[198:201], v[118:121]
	v_mfma_f32_16x16x32_bf16 v[114:117], v[190:193], v[198:201], v[114:117]
	v_mfma_f32_16x16x32_bf16 v[102:105], v[176:179], v[214:217], v[102:105]
	v_mfma_f32_16x16x32_bf16 v[98:101], v[190:193], v[214:217], v[98:101]
	v_mfma_f32_16x16x32_bf16 v[86:89], v[176:179], v[222:225], v[86:89]
	v_mfma_f32_16x16x32_bf16 v[82:85], v[190:193], v[222:225], v[82:85]
	v_mfma_f32_16x16x32_bf16 v[70:73], v[176:179], v[230:233], v[70:73]
	v_mfma_f32_16x16x32_bf16 v[66:69], v[190:193], v[230:233], v[66:69]
	s_barrier
	s_setprio 0
	s_add_i32 s45, s45, s44
	v_lshl_add_u64 v[202:203], s[30:31], 0, v[148:149]
	s_mov_b32 m0, s45
	ds_read_b128 v[194:197], v185 offset:16384
	ds_read_b128 v[198:201], v185 offset:17408
	ds_read_b128 v[210:213], v185 offset:18432
	ds_read_b128 v[214:217], v185 offset:19456
	ds_read_b128 v[218:221], v185 offset:20480
	ds_read_b128 v[222:225], v185 offset:21504
	ds_read_b128 v[226:229], v185 offset:22528
	ds_read_b128 v[230:233], v185 offset:23552
	global_load_lds_dwordx4 v[202:203], off
	s_add_i32 m0, s45, 0x2000
	s_add_u32 s80, s30, 0x40000
	v_lshl_add_u64 v[234:235], s[30:31], 0, v[152:153]
	s_addc_u32 s81, s31, 0
	s_add_i32 s45, s75, s44
	global_load_lds_dwordx4 v[234:235], off
	v_lshl_add_u64 v[236:237], s[80:81], 0, v[148:149]
	s_mov_b32 m0, s45
	v_lshl_add_u64 v[238:239], s[34:35], 0, v[150:151]
	global_load_lds_dwordx4 v[236:237], off
	v_lshl_add_u64 v[236:237], s[80:81], 0, v[152:153]
	s_add_i32 m0, s45, 0x2000
	s_nop 0
	global_load_lds_dwordx4 v[236:237], off
	v_lshl_add_u64 v[236:237], s[34:35], 0, v[146:147]
	s_mov_b32 m0, s27
	s_nop 0
	global_load_lds_dwordx4 v[236:237], off
	s_mov_b32 m0, s47
	s_nop 0
	global_load_lds_dwordx4 v[238:239], off
	s_waitcnt vmcnt(8) lgkmcnt(0)
	s_barrier
; #define PG8_STAGE(bufoff, gbase, voff) do { _Pragma("unroll") for (int _i = 0; _i < 2; ++_i) \
;         __builtin_amdgcn_global_load_lds((const unsigned*)((const char*)(gbase) + (voff)[_i]), (PG8_LAS unsigned*)(lds + (bufoff) + ldsw + _i * 8192), 16, 0, 0); } while (0)
; #define PG8_LDA(dst, b, h) do { _Pragma("unroll") for (int m = 0; m < 4; ++m) _Pragma("unroll") for (int k = 0; k < 2; ++k) dst[m][k] = *(const PG8_LAS bf16x8*)(lds + PG8_SA(b, h) + aoff + m * 2048 + k * 1024); } while (0)
; #define PG8_LDB(dst, b, h) do { _Pragma("unroll") for (int n = 0; n < 2; ++n) _Pragma("unroll") for (int k = 0; k < 2; ++k) dst[n][k] = *(const PG8_LAS bf16x8*)(lds + PG8_SB(b, h) + boff + n * 2048 + k * 1024); } while (0)
; #define PG8_MMA(ai, bj, At, Bt) do { __builtin_amdgcn_s_setprio(1); _Pragma("unroll") for (int m = 0; m < 4; ++m) _Pragma("unroll") for (int n = 0; n < 2; ++n) _Pragma("unroll") for (int k = 0; k < 2; ++k) \
;         acc[ai][bj][m][n] = __builtin_amdgcn_mfma_f32_16x16x32_bf16(Bt[n][k], At[m][k], acc[ai][bj][m][n], 0, 0, 0); __builtin_amdgcn_s_setprio(0); } while (0)
; #define PG8_WAIT_V(n) asm volatile("s_waitcnt vmcnt(" #n ")" ::: "memory")
; #define PG8_WAIT_L(n) asm volatile("s_waitcnt lgkmcnt(" #n ")" ::: "memory")
; #define PG8_BAR __builtin_amdgcn_s_barrier()
; #define PG8_SCHED __builtin_amdgcn_sched_barrier(0)
; template <class Epi, class Sched, bool ALIGN_EPI = false, bool SP2 = false>
; __device__ __forceinline__ void gemm_phase(PG8_LAS unsigned char* lds, const Gemm g, const Sched& S, const Epi& E, const int wave_s) {
;     ...
;             PG8_WAIT_V(8); PG8_WAIT_L(0); PG8_BAR; PG8_MMA(1, 0, At, B0); PG8_MMA(1, 1, At, B1); PG8_BAR; PG8_SCHED;
;             PG8_LDB(B0, 1, 0); PG8_LDB(B1, 1, 1); PG8_SCHED; PG8_LDA(At, 1, 0); PG8_STAGE(PG8_SA(0, 1), a2 + hstep, voffA);
;             PG8_WAIT_V(8); PG8_WAIT_L(0); PG8_BAR; PG8_MMA(0, 0, At, B0); PG8_MMA(0, 1, At, B1); PG8_BAR; PG8_SCHED;
	s_setprio 1
	v_mfma_f32_16x16x32_bf16 v[62:65], v[130:133], v[194:197], v[62:65]
	v_mfma_f32_16x16x32_bf16 v[58:61], v[138:141], v[194:197], v[58:61]
	v_mfma_f32_16x16x32_bf16 v[46:49], v[130:133], v[210:213], v[46:49]
	v_mfma_f32_16x16x32_bf16 v[42:45], v[138:141], v[210:213], v[42:45]
	v_mfma_f32_16x16x32_bf16 v[30:33], v[130:133], v[218:221], v[30:33]
	v_mfma_f32_16x16x32_bf16 v[26:29], v[138:141], v[218:221], v[26:29]
	v_mfma_f32_16x16x32_bf16 v[14:17], v[130:133], v[226:229], v[14:17]
	v_mfma_f32_16x16x32_bf16 v[10:13], v[138:141], v[226:229], v[10:13]
	v_mfma_f32_16x16x32_bf16 v[62:65], v[134:137], v[198:201], v[62:65]
	v_mfma_f32_16x16x32_bf16 v[58:61], v[142:145], v[198:201], v[58:61]
	v_mfma_f32_16x16x32_bf16 v[46:49], v[134:137], v[214:217], v[46:49]
	v_mfma_f32_16x16x32_bf16 v[42:45], v[142:145], v[214:217], v[42:45]
	v_mfma_f32_16x16x32_bf16 v[30:33], v[134:137], v[222:225], v[30:33]
	v_mfma_f32_16x16x32_bf16 v[26:29], v[142:145], v[222:225], v[26:29]
	v_mfma_f32_16x16x32_bf16 v[14:17], v[134:137], v[230:233], v[14:17]
	v_mfma_f32_16x16x32_bf16 v[10:13], v[142:145], v[230:233], v[10:13]
	s_setprio 0
	s_setprio 1
	v_mfma_f32_16x16x32_bf16 v[54:57], v[172:175], v[194:197], v[54:57]
	v_mfma_f32_16x16x32_bf16 v[50:53], v[186:189], v[194:197], v[50:53]
	v_mfma_f32_16x16x32_bf16 v[38:41], v[172:175], v[210:213], v[38:41]
	v_mfma_f32_16x16x32_bf16 v[34:37], v[186:189], v[210:213], v[34:37]
	v_mfma_f32_16x16x32_bf16 v[22:25], v[172:175], v[218:221], v[22:25]
	v_mfma_f32_16x16x32_bf16 v[18:21], v[186:189], v[218:221], v[18:21]
	v_mfma_f32_16x16x32_bf16 v[6:9], v[172:175], v[226:229], v[6:9]
	v_mfma_f32_16x16x32_bf16 v[2:5], v[186:189], v[226:229], v[2:5]
	v_mfma_f32_16x16x32_bf16 v[54:57], v[176:179], v[198:201], v[54:57]
	v_mfma_f32_16x16x32_bf16 v[50:53], v[190:193], v[198:201], v[50:53]
	v_mfma_f32_16x16x32_bf16 v[38:41], v[176:179], v[214:217], v[38:41]
	v_mfma_f32_16x16x32_bf16 v[34:37], v[190:193], v[214:217], v[34:37]
	v_mfma_f32_16x16x32_bf16 v[22:25], v[176:179], v[222:225], v[22:25]
	v_mfma_f32_16x16x32_bf16 v[18:21], v[190:193], v[222:225], v[18:21]
	v_mfma_f32_16x16x32_bf16 v[6:9], v[176:179], v[230:233], v[6:9]
	v_mfma_f32_16x16x32_bf16 v[2:5], v[190:193], v[230:233], v[2:5]
	s_barrier
	s_setprio 0
	s_add_i32 s45, 0, 0x18000
	v_add_u32_e32 v0, s45, v181
	s_add_i32 s75, 0, 0x1c000
	ds_read_b128 v[130:133], v0
	ds_read_b128 v[134:137], v0 offset:1024
	ds_read_b128 v[138:141], v0 offset:2048
	ds_read_b128 v[142:145], v0 offset:3072
	v_add_u32_e32 v0, s75, v181
	ds_read_b128 v[172:175], v0
	ds_read_b128 v[176:179], v0 offset:1024
	ds_read_b128 v[186:189], v0 offset:2048
	ds_read_b128 v[190:193], v0 offset:3072
	s_add_u32 s34, s34, 0x40000
	s_addc_u32 s35, s35, 0
	s_mov_b32 m0, s48
	v_lshl_add_u64 v[240:241], s[34:35], 0, v[146:147]
	ds_read_b128 v[194:197], v185 offset:32768
	ds_read_b128 v[198:201], v185 offset:33792
	ds_read_b128 v[210:213], v185 offset:34816
	ds_read_b128 v[214:217], v185 offset:35840
	ds_read_b128 v[218:221], v185 offset:36864
	ds_read_b128 v[222:225], v185 offset:37888
	ds_read_b128 v[226:229], v185 offset:38912
	ds_read_b128 v[230:233], v185 offset:39936
	global_load_lds_dwordx4 v[240:241], off
	v_lshl_add_u64 v[240:241], s[34:35], 0, v[150:151]
	s_mov_b32 m0, s49
	s_nop 0
	global_load_lds_dwordx4 v[240:241], off
	s_waitcnt vmcnt(8) lgkmcnt(0)
	s_barrier
	s_setprio 1
	v_mfma_f32_16x16x32_bf16 v[126:129], v[130:133], v[194:197], v[126:129]
	v_mfma_f32_16x16x32_bf16 v[122:125], v[138:141], v[194:197], v[122:125]
	v_mfma_f32_16x16x32_bf16 v[110:113], v[130:133], v[210:213], v[110:113]
	v_mfma_f32_16x16x32_bf16 v[106:109], v[138:141], v[210:213], v[106:109]
	v_mfma_f32_16x16x32_bf16 v[94:97], v[130:133], v[218:221], v[94:97]
	v_mfma_f32_16x16x32_bf16 v[90:93], v[138:141], v[218:221], v[90:93]
	v_mfma_f32_16x16x32_bf16 v[78:81], v[130:133], v[226:229], v[78:81]
	v_mfma_f32_16x16x32_bf16 v[74:77], v[138:141], v[226:229], v[74:77]
	v_mfma_f32_16x16x32_bf16 v[126:129], v[134:137], v[198:201], v[126:129]
	v_mfma_f32_16x16x32_bf16 v[122:125], v[142:145], v[198:201], v[122:125]
	v_mfma_f32_16x16x32_bf16 v[110:113], v[134:137], v[214:217], v[110:113]
	v_mfma_f32_16x16x32_bf16 v[106:109], v[142:145], v[214:217], v[106:109]
	v_mfma_f32_16x16x32_bf16 v[94:97], v[134:137], v[222:225], v[94:97]
	v_mfma_f32_16x16x32_bf16 v[90:93], v[142:145], v[222:225], v[90:93]
	v_mfma_f32_16x16x32_bf16 v[78:81], v[134:137], v[230:233], v[78:81]
	v_mfma_f32_16x16x32_bf16 v[74:77], v[142:145], v[230:233], v[74:77]
	s_setprio 0
	s_setprio 1
	v_mfma_f32_16x16x32_bf16 v[118:121], v[172:175], v[194:197], v[118:121]
	v_mfma_f32_16x16x32_bf16 v[114:117], v[186:189], v[194:197], v[114:117]
	v_mfma_f32_16x16x32_bf16 v[102:105], v[172:175], v[210:213], v[102:105]
	v_mfma_f32_16x16x32_bf16 v[98:101], v[186:189], v[210:213], v[98:101]
	v_mfma_f32_16x16x32_bf16 v[86:89], v[172:175], v[218:221], v[86:89]
	v_mfma_f32_16x16x32_bf16 v[82:85], v[186:189], v[218:221], v[82:85]
	v_mfma_f32_16x16x32_bf16 v[70:73], v[172:175], v[226:229], v[70:73]
	v_mfma_f32_16x16x32_bf16 v[66:69], v[186:189], v[226:229], v[66:69]
	v_mfma_f32_16x16x32_bf16 v[118:121], v[176:179], v[198:201], v[118:121]
	v_mfma_f32_16x16x32_bf16 v[114:117], v[190:193], v[198:201], v[114:117]
	v_mfma_f32_16x16x32_bf16 v[102:105], v[176:179], v[214:217], v[102:105]
	v_mfma_f32_16x16x32_bf16 v[98:101], v[190:193], v[214:217], v[98:101]
	v_mfma_f32_16x16x32_bf16 v[86:89], v[176:179], v[222:225], v[86:89]
	v_mfma_f32_16x16x32_bf16 v[82:85], v[190:193], v[222:225], v[82:85]
	v_mfma_f32_16x16x32_bf16 v[70:73], v[176:179], v[230:233], v[70:73]
	v_mfma_f32_16x16x32_bf16 v[66:69], v[190:193], v[230:233], v[66:69]
	s_barrier
; #define PG8_STAGE(bufoff, gbase, voff) do { _Pragma("unroll") for (int _i = 0; _i < 2; ++_i) \
;         __builtin_amdgcn_global_load_lds((const unsigned*)((const char*)(gbase) + (voff)[_i]), (PG8_LAS unsigned*)(lds + (bufoff) + ldsw + _i * 8192), 16, 0, 0); } while (0)
; #define PG8_LDA(dst, b, h) do { _Pragma("unroll") for (int m = 0; m < 4; ++m) _Pragma("unroll") for (int k = 0; k < 2; ++k) dst[m][k] = *(const PG8_LAS bf16x8*)(lds + PG8_SA(b, h) + aoff + m * 2048 + k * 1024); } while (0)
; #define PG8_MMA(ai, bj, At, Bt) do { __builtin_amdgcn_s_setprio(1); _Pragma("unroll") for (int m = 0; m < 4; ++m) _Pragma("unroll") for (int n = 0; n < 2; ++n) _Pragma("unroll") for (int k = 0; k < 2; ++k) \
;         acc[ai][bj][m][n] = __builtin_amdgcn_mfma_f32_16x16x32_bf16(Bt[n][k], At[m][k], acc[ai][bj][m][n], 0, 0, 0); __builtin_amdgcn_s_setprio(0); } while (0)
; #define PG8_WAIT_V(n) asm volatile("s_waitcnt vmcnt(" #n ")" ::: "memory")
; #define PG8_WAIT_L(n) asm volatile("s_waitcnt lgkmcnt(" #n ")" ::: "memory")
; #define PG8_BAR __builtin_amdgcn_s_barrier()
; #define PG8_SCHED __builtin_amdgcn_sched_barrier(0)
; template <class Epi, class Sched, bool ALIGN_EPI = false, bool SP2 = false>
; __device__ __forceinline__ void gemm_phase(PG8_LAS unsigned char* lds, const Gemm g, const Sched& S, const Epi& E, const int wave_s) {
;     ...
;             PG8_LDA(At, 1, 1); PG8_STAGE(PG8_SB(1, 0), b3, voffB); PG8_STAGE(PG8_SB(1, 1), b3 + hstep, voffB); PG8_STAGE(PG8_SA(1, 0), a3, voffA);
;             PG8_WAIT_V(8); PG8_WAIT_L(0); PG8_BAR; PG8_MMA(1, 0, At, B0); PG8_MMA(1, 1, At, B1); PG8_BAR; PG8_SCHED;
;     ...
;         if constexpr (ALIGN_EPI) { if (wr == 0) PG8_BAR; }
	s_setprio 0
	s_add_i32 s34, s45, s44
	v_lshl_add_u64 v[202:203], v[202:203], 0, s[70:71]
	s_mov_b32 m0, s34
	ds_read_b128 v[194:197], v185 offset:49152
	ds_read_b128 v[198:201], v185 offset:50176
	ds_read_b128 v[210:213], v185 offset:51200
	ds_read_b128 v[214:217], v185 offset:52224
	ds_read_b128 v[218:221], v185 offset:53248
	ds_read_b128 v[222:225], v185 offset:54272
	ds_read_b128 v[226:229], v185 offset:55296
	ds_read_b128 v[230:233], v185 offset:56320
	global_load_lds_dwordx4 v[202:203], off
	s_add_i32 m0, s34, 0x2000
	s_add_u32 s30, s30, 0x40080
	v_lshl_add_u64 v[202:203], v[234:235], 0, s[70:71]
	s_addc_u32 s31, s31, 0
	s_add_i32 s34, s75, s44
	global_load_lds_dwordx4 v[202:203], off
	v_lshl_add_u64 v[202:203], s[30:31], 0, v[148:149]
	s_mov_b32 m0, s34
	s_nop 0
	global_load_lds_dwordx4 v[202:203], off
	v_lshl_add_u64 v[202:203], s[30:31], 0, v[152:153]
	s_add_i32 m0, s34, 0x2000
	s_nop 0
	global_load_lds_dwordx4 v[202:203], off
	v_lshl_add_u64 v[202:203], v[236:237], 0, s[70:71]
	s_mov_b32 m0, s88
	s_nop 0
	global_load_lds_dwordx4 v[202:203], off
	v_lshl_add_u64 v[202:203], v[238:239], 0, s[70:71]
	s_mov_b32 m0, s89
	s_nop 0
	global_load_lds_dwordx4 v[202:203], off
	s_waitcnt vmcnt(8) lgkmcnt(0)
	s_barrier
	s_setprio 1
	v_mfma_f32_16x16x32_bf16 v[62:65], v[130:133], v[194:197], v[62:65]
	v_mfma_f32_16x16x32_bf16 v[58:61], v[138:141], v[194:197], v[58:61]
	v_mfma_f32_16x16x32_bf16 v[46:49], v[130:133], v[210:213], v[46:49]
	v_mfma_f32_16x16x32_bf16 v[42:45], v[138:141], v[210:213], v[42:45]
	v_mfma_f32_16x16x32_bf16 v[30:33], v[130:133], v[218:221], v[30:33]
	v_mfma_f32_16x16x32_bf16 v[26:29], v[138:141], v[218:221], v[26:29]
	v_mfma_f32_16x16x32_bf16 v[14:17], v[130:133], v[226:229], v[14:17]
	v_mfma_f32_16x16x32_bf16 v[10:13], v[138:141], v[226:229], v[10:13]
	v_mfma_f32_16x16x32_bf16 v[62:65], v[134:137], v[198:201], v[62:65]
	v_mfma_f32_16x16x32_bf16 v[58:61], v[142:145], v[198:201], v[58:61]
	v_mfma_f32_16x16x32_bf16 v[46:49], v[134:137], v[214:217], v[46:49]
	v_mfma_f32_16x16x32_bf16 v[42:45], v[142:145], v[214:217], v[42:45]
	v_mfma_f32_16x16x32_bf16 v[30:33], v[134:137], v[222:225], v[30:33]
	v_mfma_f32_16x16x32_bf16 v[26:29], v[142:145], v[222:225], v[26:29]
	v_mfma_f32_16x16x32_bf16 v[14:17], v[134:137], v[230:233], v[14:17]
	v_mfma_f32_16x16x32_bf16 v[10:13], v[142:145], v[230:233], v[10:13]
	s_setprio 0
	s_setprio 1
	v_mfma_f32_16x16x32_bf16 v[54:57], v[172:175], v[194:197], v[54:57]
	v_mfma_f32_16x16x32_bf16 v[50:53], v[186:189], v[194:197], v[50:53]
	v_mfma_f32_16x16x32_bf16 v[38:41], v[172:175], v[210:213], v[38:41]
	v_mfma_f32_16x16x32_bf16 v[34:37], v[186:189], v[210:213], v[34:37]
	v_mfma_f32_16x16x32_bf16 v[22:25], v[172:175], v[218:221], v[22:25]
	v_mfma_f32_16x16x32_bf16 v[18:21], v[186:189], v[218:221], v[18:21]
	v_mfma_f32_16x16x32_bf16 v[6:9], v[172:175], v[226:229], v[6:9]
	v_mfma_f32_16x16x32_bf16 v[2:5], v[186:189], v[226:229], v[2:5]
	v_mfma_f32_16x16x32_bf16 v[54:57], v[176:179], v[198:201], v[54:57]
	v_mfma_f32_16x16x32_bf16 v[50:53], v[190:193], v[198:201], v[50:53]
	v_mfma_f32_16x16x32_bf16 v[38:41], v[176:179], v[214:217], v[38:41]
	v_mfma_f32_16x16x32_bf16 v[34:37], v[190:193], v[214:217], v[34:37]
	v_mfma_f32_16x16x32_bf16 v[22:25], v[176:179], v[222:225], v[22:25]
	v_mfma_f32_16x16x32_bf16 v[18:21], v[190:193], v[222:225], v[18:21]
	v_mfma_f32_16x16x32_bf16 v[6:9], v[176:179], v[230:233], v[6:9]
	v_mfma_f32_16x16x32_bf16 v[2:5], v[190:193], v[230:233], v[2:5]
	s_barrier
	s_setprio 0
	s_add_i32 s68, s68, 2
	s_add_u32 s28, s28, 0x100
	s_addc_u32 s29, s29, 0
	s_add_u32 s64, s64, 0x100
	s_addc_u32 s65, s65, 0
	s_cmp_gt_u32 s68, 13
	s_cbranch_scc0 .LBB0_325
	s_and_b64 vcc, exec, s[14:15]
	s_cbranch_vccz .LBB0_328
	s_barrier

; #define MFMA32(a, b, c) __builtin_amdgcn_mfma_f32_32x32x16_bf16((a), (b), (c), 0, 0, 0)
; DI unsigned cvtpk(float lo, float hi) { f32x2_t v = {lo, hi}; bf16x2_t b = __builtin_convertvector(v, bf16x2_t); return __builtin_bit_cast(unsigned, b); }
; DI float bperm(float v, int x32) { return __builtin_bit_cast(float, __builtin_amdgcn_ds_bpermute(x32, __builtin_bit_cast(int, v))); }
; DI void pv_regs(const bf16x8 (&vf)[4], const f32x16& p, f32x16& O0, f32x16& O1) {
;     v4u pk; pk.x = cvtpk(p[0], p[1]); pk.y = cvtpk(p[2], p[3]); pk.z = cvtpk(p[4], p[5]); pk.w = cvtpk(p[6], p[7]);
;     const bf16x8 pb0 = __builtin_bit_cast(bf16x8, pk);
;     pk.x = cvtpk(p[8], p[9]); pk.y = cvtpk(p[10], p[11]); pk.z = cvtpk(p[12], p[13]); pk.w = cvtpk(p[14], p[15]);
;     const bf16x8 pb1 = __builtin_bit_cast(bf16x8, pk);
;     O0 = MFMA32(vf[0], pb0, O0); O1 = MFMA32(vf[2], pb0, O1);
;     O0 = MFMA32(vf[1], pb1, O0); O1 = MFMA32(vf[3], pb1, O1);
; }
; template <int MODE>
; DI bool attn_tile(const bf16x8 (&kf)[4], const bf16x8 (&vf)[4], const bf16x8 (&qf)[4], int key0, int q0, int tq, int hi, int x32, int own, unsigned selmask,
;                   float& m_run, float& l_run, f32x16& O0, f32x16& O1) {
;     ...
;         float s_lo = 0.f, s_hi = 0.f;
; #pragma unroll
;         for (int i = 0; i < 8; ++i) { s_lo += lk[i]; s_hi += lk[8 + i]; }
;         const float p_lo = bperm(s_lo, x32), p_hi = bperm(s_hi, x32);
;         const float carry = m_run;
;         float off_hi = hi ? carry : carry + p_hi;
;         float off_lo = hi ? carry + s_hi + p_hi : carry + p_hi + s_hi + p_lo;
; #pragma unroll
;         for (int i = 7; i >= 0; --i) { s[8 + i] = __builtin_amdgcn_exp2f(s[8 + i] + off_hi); off_hi += lk[8 + i]; s[i] = __builtin_amdgcn_exp2f(s[i] + off_lo); off_lo += lk[i]; }
;         m_run = carry + ((s_lo + s_hi) + (p_lo + p_hi));
;         pv_regs(vf, s, O0, O1);
;         return __all(m_run < -36.f);
.LBB0_528:
	s_nop 8
	v_add_f32_e32 v35, v59, v58
	v_add_f32_e32 v35, v60, v35
	v_add_f32_e32 v34, v51, v50
	v_add_f32_e32 v35, v61, v35
	v_add_f32_e32 v34, v52, v34
	v_add_f32_e32 v35, v62, v35
	v_add_f32_e32 v34, v53, v34
	v_add_f32_e32 v35, v63, v35
	v_add_f32_e32 v34, v54, v34
	v_add_f32_e32 v36, v64, v35
	v_add_f32_e32 v34, v55, v34
	v_add_f32_e32 v37, v65, v36
	v_add_f32_e32 v34, v56, v34
	ds_bpermute_b32 v36, v122, v37
	v_add_f32_e32 v35, v57, v34
	ds_bpermute_b32 v34, v122, v35
	v_add_f32_e32 v40, v0, v37
	s_mov_b32 s45, 0xc2100000
	s_waitcnt lgkmcnt(1)
	v_add_f32_e32 v38, v0, v36
	v_cndmask_b32_e64 v39, v0, v38, s[38:39]
	v_add_f32_e32 v38, v38, v37
	v_add_f32_e32 v40, v40, v36
	s_waitcnt lgkmcnt(0)
	v_add_f32_e32 v38, v38, v34
	v_cndmask_b32_e64 v38, v40, v38, s[38:39]
	v_add_f32_e32 v40, v81, v39
	v_exp_f32_e32 v41, v40
	v_add_f32_e32 v40, v73, v38
	v_add_f32_e32 v38, v57, v38
	v_add_f32_e32 v43, v72, v38
	v_add_f32_e32 v38, v56, v38
	v_add_f32_e32 v45, v71, v38
	v_add_f32_e32 v38, v55, v38
	v_add_f32_e32 v47, v70, v38
	v_add_f32_e32 v38, v54, v38
	v_add_f32_e32 v49, v69, v38
	v_add_f32_e32 v38, v53, v38
	v_add_f32_e32 v53, v68, v38
	v_add_f32_e32 v38, v52, v38
	v_add_f32_e32 v54, v67, v38
	v_add_f32_e32 v38, v51, v38
	v_add_f32_e32 v38, v66, v38
	v_add_f32_e32 v39, v65, v39
	v_exp_f32_e32 v40, v40
	v_exp_f32_e32 v43, v43
	v_exp_f32_e32 v45, v45
	v_exp_f32_e32 v47, v47
	v_exp_f32_e32 v49, v49
	v_exp_f32_e32 v53, v53
	v_exp_f32_e32 v54, v54
	v_exp_f32_e32 v38, v38
	v_add_f32_e32 v42, v80, v39
	v_add_f32_e32 v39, v64, v39
	v_add_f32_e32 v44, v79, v39
	v_add_f32_e32 v39, v63, v39
	v_pk_add_f32 v[34:35], v[34:35], v[36:37]
	v_add_f32_e32 v46, v78, v39
	v_add_f32_e32 v39, v62, v39
	v_add_f32_e32 v34, v34, v35
	v_add_f32_e32 v48, v77, v39
	v_add_f32_e32 v39, v61, v39
	v_add_f32_e32 v0, v0, v34
	v_cvt_pk_bf16_f32 v34, v38, v54
	v_cvt_pk_bf16_f32 v35, v53, v49
	v_cvt_pk_bf16_f32 v36, v47, v45
	v_cvt_pk_bf16_f32 v37, v43, v40
	v_add_f32_e32 v50, v76, v39
	v_add_f32_e32 v39, v60, v39
	v_mfma_f32_32x32x16_bf16 v[2:17], v[110:113], v[34:37], v[2:17]
	v_add_f32_e32 v52, v75, v39
	v_add_f32_e32 v39, v59, v39
	v_add_f32_e32 v39, v74, v39
	v_exp_f32_e32 v42, v42
	v_exp_f32_e32 v44, v44
	v_exp_f32_e32 v46, v46
	v_exp_f32_e32 v48, v48
	v_mfma_f32_32x32x16_bf16 v[18:33], v[106:109], v[34:37], v[18:33]
	v_exp_f32_e32 v50, v50
	v_exp_f32_e32 v52, v52
	v_exp_f32_e32 v39, v39
	v_cvt_pk_bf16_f32 v40, v46, v44
	v_cvt_pk_bf16_f32 v41, v42, v41
	v_cmp_gt_f32_e32 vcc, s45, v0
	v_cvt_pk_bf16_f32 v38, v39, v52
	v_cvt_pk_bf16_f32 v39, v50, v48
	s_cmp_lg_u64 vcc, exec
	s_cselect_b64 s[46:47], -1, 0
	v_mfma_f32_32x32x16_bf16 v[2:17], v[102:105], v[38:41], v[2:17]
	s_cmp_lg_u32 s97, 0
	s_cselect_b64 s[80:81], -1, 0
	s_and_b64 s[46:47], s[80:81], s[46:47]
	s_addk_i32 s59, 0xe000
	v_lshl_add_u64 v[116:117], v[116:117], 0, s[78:79]
	v_lshl_add_u64 v[118:119], v[118:119], 0, s[78:79]
	s_and_b64 vcc, exec, s[46:47]
	v_mfma_f32_32x32x16_bf16 v[18:33], v[98:101], v[38:41], v[18:33]
	s_cbranch_vccz .LBB0_523

; #define PG8_STAGE(bufoff, gbase, voff) do { _Pragma("unroll") for (int _i = 0; _i < 2; ++_i) \
;         __builtin_amdgcn_global_load_lds((const unsigned*)((const char*)(gbase) + (voff)[_i]), (PG8_LAS unsigned*)(lds + (bufoff) + ldsw + _i * 8192), 16, 0, 0); } while (0)
; #define PG8_LDA(dst, b, h) do { _Pragma("unroll") for (int m = 0; m < 4; ++m) _Pragma("unroll") for (int k = 0; k < 2; ++k) dst[m][k] = *(const PG8_LAS bf16x8*)(lds + PG8_SA(b, h) + aoff + m * 2048 + k * 1024); } while (0)
; #define PG8_LDB(dst, b, h) do { _Pragma("unroll") for (int n = 0; n < 2; ++n) _Pragma("unroll") for (int k = 0; k < 2; ++k) dst[n][k] = *(const PG8_LAS bf16x8*)(lds + PG8_SB(b, h) + boff + n * 2048 + k * 1024); } while (0)
; #define PG8_MMA(ai, bj, At, Bt) do { __builtin_amdgcn_s_setprio(1); _Pragma("unroll") for (int m = 0; m < 4; ++m) _Pragma("unroll") for (int n = 0; n < 2; ++n) _Pragma("unroll") for (int k = 0; k < 2; ++k) \
;         acc[ai][bj][m][n] = __builtin_amdgcn_mfma_f32_16x16x32_bf16(Bt[n][k], At[m][k], acc[ai][bj][m][n], 0, 0, 0); __builtin_amdgcn_s_setprio(0); } while (0)
; #define PG8_WAIT_V(n) asm volatile("s_waitcnt vmcnt(" #n ")" ::: "memory")
; #define PG8_WAIT_L(n) asm volatile("s_waitcnt lgkmcnt(" #n ")" ::: "memory")
; #define PG8_BAR __builtin_amdgcn_s_barrier()
; template <class Epi, class Sched, bool ALIGN_EPI = false, bool SP2 = false>
; __device__ __forceinline__ void gemm_phase(PG8_LAS unsigned char* lds, const Gemm g, const Sched& S, const Epi& E, const int wave_s) {
;     ...
;         for (int t = 0; t < nt; t += 2) {
;             const bool last = (t == nt - 2);
;             const char* a1 = cA + (size_t)(t + 1) * kstep;
;             const char* a2 = last ? nA : cA + (size_t)(t + 2) * kstep; const char* b2 = last ? nB : cB + (size_t)(t + 2) * kstep;
;             const char* a3 = a2 + kstep; const char* b3 = b2 + kstep;
;             if (last && has_next) S.a_ready(nxt);
;             if constexpr (SP2) {
;             PG8_LDB(B0, 0, 0); PG8_LDB(B1, 0, 1); PG8_SCHED; PG8_LDA(At, 0, 0); PG8_STAGE(PG8_SA(1, 1), a1 + hstep, voffA);
;             PG8_WAIT_V(8); PG8_WAIT_L(0); PG8_BAR; PG8_MMA(0, 0, At, B0); PG8_MMA(0, 1, At, B1); PG8_BAR; PG8_SCHED;
;             PG8_LDA(At, 0, 1); PG8_STAGE(PG8_SB(0, 0), b2, voffB); PG8_STAGE(PG8_SB(0, 1), b2 + hstep, voffB); PG8_STAGE(PG8_SA(0, 0), a2, voffA);
.LBB0_658:
	s_add_u32 s36, s34, 0xfffc0080
	s_addc_u32 s37, s35, -1
	s_add_i32 s45, 0, 0x10000
	s_cmp_eq_u32 s50, 12
	s_cselect_b32 s41, s27, s37
	s_cselect_b32 s40, s55, s36
	v_add_u32_e32 v152, s45, v195
	s_cselect_b32 s37, s25, vcc_hi
	s_cselect_b32 s36, s97, vcc_lo
	s_add_i32 s75, 0, 0x14000
	ds_read_b128 v[94:97], v152
	ds_read_b128 v[98:101], v152 offset:1024
	ds_read_b128 v[148:151], v152 offset:2048
	ds_read_b128 v[162:165], v152 offset:3072
	v_add_u32_e32 v152, s75, v195
	ds_read_b128 v[166:169], v152
	ds_read_b128 v[170:173], v152 offset:1024
	ds_read_b128 v[174:177], v152 offset:2048
	ds_read_b128 v[178:181], v152 offset:3072
	v_lshl_add_u64 v[152:153], s[34:35], 0, v[144:145]
	s_add_i32 m0, s88, 0xc000
	ds_read_b128 v[182:185], v198
	ds_read_b128 v[186:189], v198 offset:1024
	ds_read_b128 v[190:193], v198 offset:2048
	ds_read_b128 v[200:203], v198 offset:3072
	ds_read_b128 v[210:213], v198 offset:4096
	ds_read_b128 v[214:217], v198 offset:5120
	ds_read_b128 v[218:221], v198 offset:6144
	ds_read_b128 v[222:225], v198 offset:7168
	global_load_lds_dwordx4 v[152:153], off
	v_lshl_add_u64 v[152:153], s[34:35], 0, v[146:147]
	s_add_i32 m0, s88, 0xe000
	s_nop 0
	global_load_lds_dwordx4 v[152:153], off
	s_waitcnt vmcnt(8) lgkmcnt(0)
	s_barrier
	s_setprio 1
	v_mfma_f32_16x16x32_bf16 v[134:137], v[94:97], v[182:185], v[134:137]
	v_mfma_f32_16x16x32_bf16 v[130:133], v[148:151], v[182:185], v[130:133]
	v_mfma_f32_16x16x32_bf16 v[126:129], v[94:97], v[190:193], v[126:129]
	v_mfma_f32_16x16x32_bf16 v[122:125], v[148:151], v[190:193], v[122:125]
	v_mfma_f32_16x16x32_bf16 v[118:121], v[94:97], v[210:213], v[118:121]
	v_mfma_f32_16x16x32_bf16 v[114:117], v[148:151], v[210:213], v[114:117]
	v_mfma_f32_16x16x32_bf16 v[110:113], v[94:97], v[218:221], v[110:113]
	v_mfma_f32_16x16x32_bf16 v[106:109], v[148:151], v[218:221], v[106:109]
	v_mfma_f32_16x16x32_bf16 v[134:137], v[98:101], v[186:189], v[134:137]
	v_mfma_f32_16x16x32_bf16 v[130:133], v[162:165], v[186:189], v[130:133]
	v_mfma_f32_16x16x32_bf16 v[126:129], v[98:101], v[200:203], v[126:129]
	v_mfma_f32_16x16x32_bf16 v[122:125], v[162:165], v[200:203], v[122:125]
	v_mfma_f32_16x16x32_bf16 v[118:121], v[98:101], v[214:217], v[118:121]
	v_mfma_f32_16x16x32_bf16 v[114:117], v[162:165], v[214:217], v[114:117]
	v_mfma_f32_16x16x32_bf16 v[110:113], v[98:101], v[222:225], v[110:113]
	v_mfma_f32_16x16x32_bf16 v[106:109], v[162:165], v[222:225], v[106:109]
	s_setprio 0
	s_setprio 1
	v_mfma_f32_16x16x32_bf16 v[58:61], v[166:169], v[182:185], v[58:61]
	v_mfma_f32_16x16x32_bf16 v[62:65], v[174:177], v[182:185], v[62:65]
	v_mfma_f32_16x16x32_bf16 v[54:57], v[166:169], v[190:193], v[54:57]
	v_mfma_f32_16x16x32_bf16 v[50:53], v[174:177], v[190:193], v[50:53]
	v_mfma_f32_16x16x32_bf16 v[46:49], v[166:169], v[210:213], v[46:49]
	v_mfma_f32_16x16x32_bf16 v[42:45], v[174:177], v[210:213], v[42:45]
	v_mfma_f32_16x16x32_bf16 v[38:41], v[166:169], v[218:221], v[38:41]
	v_mfma_f32_16x16x32_bf16 v[34:37], v[174:177], v[218:221], v[34:37]
	v_mfma_f32_16x16x32_bf16 v[58:61], v[170:173], v[186:189], v[58:61]
	v_mfma_f32_16x16x32_bf16 v[62:65], v[178:181], v[186:189], v[62:65]
	v_mfma_f32_16x16x32_bf16 v[54:57], v[170:173], v[200:203], v[54:57]
	v_mfma_f32_16x16x32_bf16 v[50:53], v[178:181], v[200:203], v[50:53]
	v_mfma_f32_16x16x32_bf16 v[46:49], v[170:173], v[214:217], v[46:49]
	v_mfma_f32_16x16x32_bf16 v[42:45], v[178:181], v[214:217], v[42:45]
	v_mfma_f32_16x16x32_bf16 v[38:41], v[170:173], v[222:225], v[38:41]
	v_mfma_f32_16x16x32_bf16 v[34:37], v[178:181], v[222:225], v[34:37]
	s_barrier
	s_setprio 0
	s_add_i32 s45, s45, s68
	v_lshl_add_u64 v[152:153], s[36:37], 0, v[0:1]
	s_mov_b32 m0, s45
	ds_read_b128 v[182:185], v198 offset:16384
	ds_read_b128 v[186:189], v198 offset:17408
	ds_read_b128 v[190:193], v198 offset:18432
	ds_read_b128 v[200:203], v198 offset:19456
	ds_read_b128 v[210:213], v198 offset:20480
	ds_read_b128 v[214:217], v198 offset:21504
	ds_read_b128 v[218:221], v198 offset:22528
	ds_read_b128 v[222:225], v198 offset:23552
	global_load_lds_dwordx4 v[152:153], off
	s_add_i32 m0, s45, 0x2000
	s_add_u32 s80, s36, 0x40000
	v_lshl_add_u64 v[226:227], s[36:37], 0, v[138:139]
	s_addc_u32 s81, s37, 0
	s_add_i32 s45, s75, s68
	global_load_lds_dwordx4 v[226:227], off
	v_lshl_add_u64 v[228:229], s[80:81], 0, v[0:1]
	s_mov_b32 m0, s45
	v_lshl_add_u64 v[230:231], s[40:41], 0, v[140:141]
	global_load_lds_dwordx4 v[228:229], off
	v_lshl_add_u64 v[228:229], s[80:81], 0, v[138:139]
	s_add_i32 m0, s45, 0x2000
	s_nop 0
	global_load_lds_dwordx4 v[228:229], off
	v_lshl_add_u64 v[228:229], s[40:41], 0, v[142:143]
	s_mov_b32 m0, s88
	s_nop 0
	global_load_lds_dwordx4 v[228:229], off
	s_mov_b32 m0, s89
	s_nop 0
	global_load_lds_dwordx4 v[230:231], off
	s_waitcnt vmcnt(8) lgkmcnt(0)
	s_barrier
; #define PG8_STAGE(bufoff, gbase, voff) do { _Pragma("unroll") for (int _i = 0; _i < 2; ++_i) \
;         __builtin_amdgcn_global_load_lds((const unsigned*)((const char*)(gbase) + (voff)[_i]), (PG8_LAS unsigned*)(lds + (bufoff) + ldsw + _i * 8192), 16, 0, 0); } while (0)
; #define PG8_LDA(dst, b, h) do { _Pragma("unroll") for (int m = 0; m < 4; ++m) _Pragma("unroll") for (int k = 0; k < 2; ++k) dst[m][k] = *(const PG8_LAS bf16x8*)(lds + PG8_SA(b, h) + aoff + m * 2048 + k * 1024); } while (0)
; #define PG8_LDB(dst, b, h) do { _Pragma("unroll") for (int n = 0; n < 2; ++n) _Pragma("unroll") for (int k = 0; k < 2; ++k) dst[n][k] = *(const PG8_LAS bf16x8*)(lds + PG8_SB(b, h) + boff + n * 2048 + k * 1024); } while (0)
; #define PG8_MMA(ai, bj, At, Bt) do { __builtin_amdgcn_s_setprio(1); _Pragma("unroll") for (int m = 0; m < 4; ++m) _Pragma("unroll") for (int n = 0; n < 2; ++n) _Pragma("unroll") for (int k = 0; k < 2; ++k) \
;         acc[ai][bj][m][n] = __builtin_amdgcn_mfma_f32_16x16x32_bf16(Bt[n][k], At[m][k], acc[ai][bj][m][n], 0, 0, 0); __builtin_amdgcn_s_setprio(0); } while (0)
; #define PG8_WAIT_V(n) asm volatile("s_waitcnt vmcnt(" #n ")" ::: "memory")
; #define PG8_WAIT_L(n) asm volatile("s_waitcnt lgkmcnt(" #n ")" ::: "memory")
; #define PG8_BAR __builtin_amdgcn_s_barrier()
; #define PG8_SCHED __builtin_amdgcn_sched_barrier(0)
; template <class Epi, class Sched, bool ALIGN_EPI = false, bool SP2 = false>
; __device__ __forceinline__ void gemm_phase(PG8_LAS unsigned char* lds, const Gemm g, const Sched& S, const Epi& E, const int wave_s) {
;     ...
;             PG8_WAIT_V(8); PG8_WAIT_L(0); PG8_BAR; PG8_MMA(1, 0, At, B0); PG8_MMA(1, 1, At, B1); PG8_BAR; PG8_SCHED;
;             PG8_LDB(B0, 1, 0); PG8_LDB(B1, 1, 1); PG8_SCHED; PG8_LDA(At, 1, 0); PG8_STAGE(PG8_SA(0, 1), a2 + hstep, voffA);
;             PG8_WAIT_V(8); PG8_WAIT_L(0); PG8_BAR; PG8_MMA(0, 0, At, B0); PG8_MMA(0, 1, At, B1); PG8_BAR; PG8_SCHED;
	s_setprio 1
	v_mfma_f32_16x16x32_bf16 v[102:105], v[94:97], v[182:185], v[102:105]
	v_mfma_f32_16x16x32_bf16 v[90:93], v[148:151], v[182:185], v[90:93]
	v_mfma_f32_16x16x32_bf16 v[86:89], v[94:97], v[190:193], v[86:89]
	v_mfma_f32_16x16x32_bf16 v[82:85], v[148:151], v[190:193], v[82:85]
	v_mfma_f32_16x16x32_bf16 v[78:81], v[94:97], v[210:213], v[78:81]
	v_mfma_f32_16x16x32_bf16 v[74:77], v[148:151], v[210:213], v[74:77]
	v_mfma_f32_16x16x32_bf16 v[70:73], v[94:97], v[218:221], v[70:73]
	v_mfma_f32_16x16x32_bf16 v[66:69], v[148:151], v[218:221], v[66:69]
	v_mfma_f32_16x16x32_bf16 v[102:105], v[98:101], v[186:189], v[102:105]
	v_mfma_f32_16x16x32_bf16 v[90:93], v[162:165], v[186:189], v[90:93]
	v_mfma_f32_16x16x32_bf16 v[86:89], v[98:101], v[200:203], v[86:89]
	v_mfma_f32_16x16x32_bf16 v[82:85], v[162:165], v[200:203], v[82:85]
	v_mfma_f32_16x16x32_bf16 v[78:81], v[98:101], v[214:217], v[78:81]
	v_mfma_f32_16x16x32_bf16 v[74:77], v[162:165], v[214:217], v[74:77]
	v_mfma_f32_16x16x32_bf16 v[70:73], v[98:101], v[222:225], v[70:73]
	v_mfma_f32_16x16x32_bf16 v[66:69], v[162:165], v[222:225], v[66:69]
	s_setprio 0
	s_setprio 1
	v_mfma_f32_16x16x32_bf16 v[30:33], v[166:169], v[182:185], v[30:33]
	v_mfma_f32_16x16x32_bf16 v[26:29], v[174:177], v[182:185], v[26:29]
	v_mfma_f32_16x16x32_bf16 v[22:25], v[166:169], v[190:193], v[22:25]
	v_mfma_f32_16x16x32_bf16 v[18:21], v[174:177], v[190:193], v[18:21]
	v_mfma_f32_16x16x32_bf16 v[14:17], v[166:169], v[210:213], v[14:17]
	v_mfma_f32_16x16x32_bf16 v[10:13], v[174:177], v[210:213], v[10:13]
	v_mfma_f32_16x16x32_bf16 v[6:9], v[166:169], v[218:221], v[6:9]
	v_mfma_f32_16x16x32_bf16 v[2:5], v[174:177], v[218:221], v[2:5]
	v_mfma_f32_16x16x32_bf16 v[30:33], v[170:173], v[186:189], v[30:33]
	v_mfma_f32_16x16x32_bf16 v[26:29], v[178:181], v[186:189], v[26:29]
	v_mfma_f32_16x16x32_bf16 v[22:25], v[170:173], v[200:203], v[22:25]
	v_mfma_f32_16x16x32_bf16 v[18:21], v[178:181], v[200:203], v[18:21]
	v_mfma_f32_16x16x32_bf16 v[14:17], v[170:173], v[214:217], v[14:17]
	v_mfma_f32_16x16x32_bf16 v[10:13], v[178:181], v[214:217], v[10:13]
	v_mfma_f32_16x16x32_bf16 v[6:9], v[170:173], v[222:225], v[6:9]
	v_mfma_f32_16x16x32_bf16 v[2:5], v[178:181], v[222:225], v[2:5]
	s_barrier
	s_setprio 0
	s_add_i32 s45, 0, 0x18000
	s_add_i32 s75, 0, 0x1c000
	v_add_u32_e32 v162, s45, v195
	v_add_u32_e32 v178, s75, v195
	ds_read_b128 v[94:97], v162
	ds_read_b128 v[98:101], v162 offset:1024
	ds_read_b128 v[148:151], v162 offset:2048
	ds_read_b128 v[162:165], v162 offset:3072
	ds_read_b128 v[166:169], v178
	ds_read_b128 v[170:173], v178 offset:1024
	ds_read_b128 v[174:177], v178 offset:2048
	ds_read_b128 v[178:181], v178 offset:3072
	s_add_u32 s40, s40, 0x40000
	s_addc_u32 s41, s41, 0
	s_mov_b32 m0, s38
	v_lshl_add_u64 v[232:233], s[40:41], 0, v[142:143]
	ds_read_b128 v[182:185], v198 offset:32768
	ds_read_b128 v[186:189], v198 offset:33792
	ds_read_b128 v[190:193], v198 offset:34816
	ds_read_b128 v[200:203], v198 offset:35840
	ds_read_b128 v[210:213], v198 offset:36864
	ds_read_b128 v[214:217], v198 offset:37888
	ds_read_b128 v[218:221], v198 offset:38912
	ds_read_b128 v[222:225], v198 offset:39936
	global_load_lds_dwordx4 v[232:233], off
	v_lshl_add_u64 v[232:233], s[40:41], 0, v[140:141]
	s_mov_b32 m0, s39
	s_nop 0
	global_load_lds_dwordx4 v[232:233], off
	s_waitcnt vmcnt(8) lgkmcnt(0)
	s_barrier
	s_setprio 1
	v_mfma_f32_16x16x32_bf16 v[134:137], v[94:97], v[182:185], v[134:137]
	v_mfma_f32_16x16x32_bf16 v[130:133], v[148:151], v[182:185], v[130:133]
	v_mfma_f32_16x16x32_bf16 v[126:129], v[94:97], v[190:193], v[126:129]
	v_mfma_f32_16x16x32_bf16 v[122:125], v[148:151], v[190:193], v[122:125]
	v_mfma_f32_16x16x32_bf16 v[118:121], v[94:97], v[210:213], v[118:121]
	v_mfma_f32_16x16x32_bf16 v[114:117], v[148:151], v[210:213], v[114:117]
	v_mfma_f32_16x16x32_bf16 v[110:113], v[94:97], v[218:221], v[110:113]
	v_mfma_f32_16x16x32_bf16 v[106:109], v[148:151], v[218:221], v[106:109]
	v_mfma_f32_16x16x32_bf16 v[134:137], v[98:101], v[186:189], v[134:137]
	v_mfma_f32_16x16x32_bf16 v[130:133], v[162:165], v[186:189], v[130:133]
	v_mfma_f32_16x16x32_bf16 v[126:129], v[98:101], v[200:203], v[126:129]
	v_mfma_f32_16x16x32_bf16 v[122:125], v[162:165], v[200:203], v[122:125]
	v_mfma_f32_16x16x32_bf16 v[118:121], v[98:101], v[214:217], v[118:121]
	v_mfma_f32_16x16x32_bf16 v[114:117], v[162:165], v[214:217], v[114:117]
	v_mfma_f32_16x16x32_bf16 v[110:113], v[98:101], v[222:225], v[110:113]
	v_mfma_f32_16x16x32_bf16 v[106:109], v[162:165], v[222:225], v[106:109]
	s_setprio 0
	s_setprio 1
	v_mfma_f32_16x16x32_bf16 v[58:61], v[166:169], v[182:185], v[58:61]
	v_mfma_f32_16x16x32_bf16 v[62:65], v[174:177], v[182:185], v[62:65]
	v_mfma_f32_16x16x32_bf16 v[54:57], v[166:169], v[190:193], v[54:57]
	v_mfma_f32_16x16x32_bf16 v[50:53], v[174:177], v[190:193], v[50:53]
	v_mfma_f32_16x16x32_bf16 v[46:49], v[166:169], v[210:213], v[46:49]
	v_mfma_f32_16x16x32_bf16 v[42:45], v[174:177], v[210:213], v[42:45]
	v_mfma_f32_16x16x32_bf16 v[38:41], v[166:169], v[218:221], v[38:41]
	v_mfma_f32_16x16x32_bf16 v[34:37], v[174:177], v[218:221], v[34:37]
	v_mfma_f32_16x16x32_bf16 v[58:61], v[170:173], v[186:189], v[58:61]
	v_mfma_f32_16x16x32_bf16 v[62:65], v[178:181], v[186:189], v[62:65]
	v_mfma_f32_16x16x32_bf16 v[54:57], v[170:173], v[200:203], v[54:57]
	v_mfma_f32_16x16x32_bf16 v[50:53], v[178:181], v[200:203], v[50:53]
	v_mfma_f32_16x16x32_bf16 v[46:49], v[170:173], v[214:217], v[46:49]
	v_mfma_f32_16x16x32_bf16 v[42:45], v[178:181], v[214:217], v[42:45]
	v_mfma_f32_16x16x32_bf16 v[38:41], v[170:173], v[222:225], v[38:41]
	v_mfma_f32_16x16x32_bf16 v[34:37], v[178:181], v[222:225], v[34:37]
	s_barrier
; #define PG8_STAGE(bufoff, gbase, voff) do { _Pragma("unroll") for (int _i = 0; _i < 2; ++_i) \
;         __builtin_amdgcn_global_load_lds((const unsigned*)((const char*)(gbase) + (voff)[_i]), (PG8_LAS unsigned*)(lds + (bufoff) + ldsw + _i * 8192), 16, 0, 0); } while (0)
; #define PG8_LDA(dst, b, h) do { _Pragma("unroll") for (int m = 0; m < 4; ++m) _Pragma("unroll") for (int k = 0; k < 2; ++k) dst[m][k] = *(const PG8_LAS bf16x8*)(lds + PG8_SA(b, h) + aoff + m * 2048 + k * 1024); } while (0)
; #define PG8_MMA(ai, bj, At, Bt) do { __builtin_amdgcn_s_setprio(1); _Pragma("unroll") for (int m = 0; m < 4; ++m) _Pragma("unroll") for (int n = 0; n < 2; ++n) _Pragma("unroll") for (int k = 0; k < 2; ++k) \
;         acc[ai][bj][m][n] = __builtin_amdgcn_mfma_f32_16x16x32_bf16(Bt[n][k], At[m][k], acc[ai][bj][m][n], 0, 0, 0); __builtin_amdgcn_s_setprio(0); } while (0)
; #define PG8_WAIT_V(n) asm volatile("s_waitcnt vmcnt(" #n ")" ::: "memory")
; #define PG8_WAIT_L(n) asm volatile("s_waitcnt lgkmcnt(" #n ")" ::: "memory")
; #define PG8_BAR __builtin_amdgcn_s_barrier()
; #define PG8_SCHED __builtin_amdgcn_sched_barrier(0)
; template <class Epi, class Sched, bool ALIGN_EPI = false, bool SP2 = false>
; __device__ __forceinline__ void gemm_phase(PG8_LAS unsigned char* lds, const Gemm g, const Sched& S, const Epi& E, const int wave_s) {
;     ...
;             PG8_LDA(At, 1, 1); PG8_STAGE(PG8_SB(1, 0), b3, voffB); PG8_STAGE(PG8_SB(1, 1), b3 + hstep, voffB); PG8_STAGE(PG8_SA(1, 0), a3, voffA);
;             PG8_WAIT_V(8); PG8_WAIT_L(0); PG8_BAR; PG8_MMA(1, 0, At, B0); PG8_MMA(1, 1, At, B1); PG8_BAR; PG8_SCHED;
;     ...
;         if constexpr (ALIGN_EPI) { if (wr == 0) PG8_BAR; }
	s_setprio 0
	s_add_i32 s40, s45, s68
	v_lshl_add_u64 v[152:153], v[152:153], 0, s[70:71]
	s_mov_b32 m0, s40
	ds_read_b128 v[182:185], v198 offset:49152
	ds_read_b128 v[186:189], v198 offset:50176
	ds_read_b128 v[190:193], v198 offset:51200
	ds_read_b128 v[200:203], v198 offset:52224
	ds_read_b128 v[210:213], v198 offset:53248
	ds_read_b128 v[214:217], v198 offset:54272
	ds_read_b128 v[218:221], v198 offset:55296
	ds_read_b128 v[222:225], v198 offset:56320
	global_load_lds_dwordx4 v[152:153], off
	s_add_i32 m0, s40, 0x2000
	s_add_u32 s36, s36, 0x40080
	v_lshl_add_u64 v[152:153], v[226:227], 0, s[70:71]
	s_addc_u32 s37, s37, 0
	s_add_i32 s40, s75, s68
	global_load_lds_dwordx4 v[152:153], off
	v_lshl_add_u64 v[152:153], s[36:37], 0, v[0:1]
	s_mov_b32 m0, s40
	s_nop 0
	global_load_lds_dwordx4 v[152:153], off
	v_lshl_add_u64 v[152:153], s[36:37], 0, v[138:139]
	s_add_i32 m0, s40, 0x2000
	s_nop 0
	global_load_lds_dwordx4 v[152:153], off
	v_lshl_add_u64 v[152:153], v[228:229], 0, s[70:71]
	s_mov_b32 m0, s44
	s_nop 0
	global_load_lds_dwordx4 v[152:153], off
	v_lshl_add_u64 v[152:153], v[230:231], 0, s[70:71]
	s_mov_b32 m0, s54
	s_nop 0
	global_load_lds_dwordx4 v[152:153], off
	s_waitcnt vmcnt(8) lgkmcnt(0)
	s_barrier
	s_setprio 1
	v_mfma_f32_16x16x32_bf16 v[102:105], v[94:97], v[182:185], v[102:105]
	v_mfma_f32_16x16x32_bf16 v[90:93], v[148:151], v[182:185], v[90:93]
	v_mfma_f32_16x16x32_bf16 v[86:89], v[94:97], v[190:193], v[86:89]
	v_mfma_f32_16x16x32_bf16 v[82:85], v[148:151], v[190:193], v[82:85]
	v_mfma_f32_16x16x32_bf16 v[78:81], v[94:97], v[210:213], v[78:81]
	v_mfma_f32_16x16x32_bf16 v[74:77], v[148:151], v[210:213], v[74:77]
	v_mfma_f32_16x16x32_bf16 v[70:73], v[94:97], v[218:221], v[70:73]
	v_mfma_f32_16x16x32_bf16 v[66:69], v[148:151], v[218:221], v[66:69]
	v_mfma_f32_16x16x32_bf16 v[102:105], v[98:101], v[186:189], v[102:105]
	v_mfma_f32_16x16x32_bf16 v[90:93], v[162:165], v[186:189], v[90:93]
	v_mfma_f32_16x16x32_bf16 v[86:89], v[98:101], v[200:203], v[86:89]
	v_mfma_f32_16x16x32_bf16 v[82:85], v[162:165], v[200:203], v[82:85]
	v_mfma_f32_16x16x32_bf16 v[78:81], v[98:101], v[214:217], v[78:81]
	v_mfma_f32_16x16x32_bf16 v[74:77], v[162:165], v[214:217], v[74:77]
	v_mfma_f32_16x16x32_bf16 v[70:73], v[98:101], v[222:225], v[70:73]
	v_mfma_f32_16x16x32_bf16 v[66:69], v[162:165], v[222:225], v[66:69]
	s_setprio 0
	s_setprio 1
	v_mfma_f32_16x16x32_bf16 v[30:33], v[166:169], v[182:185], v[30:33]
	v_mfma_f32_16x16x32_bf16 v[26:29], v[174:177], v[182:185], v[26:29]
	v_mfma_f32_16x16x32_bf16 v[22:25], v[166:169], v[190:193], v[22:25]
	v_mfma_f32_16x16x32_bf16 v[18:21], v[174:177], v[190:193], v[18:21]
	v_mfma_f32_16x16x32_bf16 v[14:17], v[166:169], v[210:213], v[14:17]
	v_mfma_f32_16x16x32_bf16 v[10:13], v[174:177], v[210:213], v[10:13]
	v_mfma_f32_16x16x32_bf16 v[6:9], v[166:169], v[218:221], v[6:9]
	v_mfma_f32_16x16x32_bf16 v[2:5], v[174:177], v[218:221], v[2:5]
	v_mfma_f32_16x16x32_bf16 v[30:33], v[170:173], v[186:189], v[30:33]
	v_mfma_f32_16x16x32_bf16 v[26:29], v[178:181], v[186:189], v[26:29]
	v_mfma_f32_16x16x32_bf16 v[22:25], v[170:173], v[200:203], v[22:25]
	v_mfma_f32_16x16x32_bf16 v[18:21], v[178:181], v[200:203], v[18:21]
	v_mfma_f32_16x16x32_bf16 v[14:17], v[170:173], v[214:217], v[14:17]
	v_mfma_f32_16x16x32_bf16 v[10:13], v[178:181], v[214:217], v[10:13]
	v_mfma_f32_16x16x32_bf16 v[6:9], v[170:173], v[222:225], v[6:9]
	v_mfma_f32_16x16x32_bf16 v[2:5], v[178:181], v[222:225], v[2:5]
	s_barrier
	s_setprio 0
	s_add_i32 s50, s50, 2
	s_add_u32 s34, s34, 0x100
	s_addc_u32 s35, s35, 0
	s_add_u32 vcc_lo, vcc_lo, 0x100
	s_addc_u32 vcc_hi, vcc_hi, 0
	s_cmp_gt_u32 s50, 13
	s_cbranch_scc0 .LBB0_658
	s_and_b64 vcc, exec, s[22:23]
	s_cbranch_vccz .LBB0_661
	s_barrier

; #define PG8_STAGE(bufoff, gbase, voff) do { _Pragma("unroll") for (int _i = 0; _i < 2; ++_i) \
;         __builtin_amdgcn_global_load_lds((const unsigned*)((const char*)(gbase) + (voff)[_i]), (PG8_LAS unsigned*)(lds + (bufoff) + ldsw + _i * 8192), 16, 0, 0); } while (0)
; #define PG8_LDA(dst, b, h) do { _Pragma("unroll") for (int m = 0; m < 4; ++m) _Pragma("unroll") for (int k = 0; k < 2; ++k) dst[m][k] = *(const PG8_LAS bf16x8*)(lds + PG8_SA(b, h) + aoff + m * 2048 + k * 1024); } while (0)
; #define PG8_LDB(dst, b, h) do { _Pragma("unroll") for (int n = 0; n < 2; ++n) _Pragma("unroll") for (int k = 0; k < 2; ++k) dst[n][k] = *(const PG8_LAS bf16x8*)(lds + PG8_SB(b, h) + boff + n * 2048 + k * 1024); } while (0)
; #define PG8_MMA(ai, bj, At, Bt) do { __builtin_amdgcn_s_setprio(1); _Pragma("unroll") for (int m = 0; m < 4; ++m) _Pragma("unroll") for (int n = 0; n < 2; ++n) _Pragma("unroll") for (int k = 0; k < 2; ++k) \
;         acc[ai][bj][m][n] = __builtin_amdgcn_mfma_f32_16x16x32_bf16(Bt[n][k], At[m][k], acc[ai][bj][m][n], 0, 0, 0); __builtin_amdgcn_s_setprio(0); } while (0)
; #define PG8_WAIT_V(n) asm volatile("s_waitcnt vmcnt(" #n ")" ::: "memory")
; #define PG8_WAIT_L(n) asm volatile("s_waitcnt lgkmcnt(" #n ")" ::: "memory")
; #define PG8_BAR __builtin_amdgcn_s_barrier()
; template <class Epi, class Sched, bool ALIGN_EPI = false, bool SP2 = false>
; __device__ __forceinline__ void gemm_phase(PG8_LAS unsigned char* lds, const Gemm g, const Sched& S, const Epi& E, const int wave_s) {
;     ...
;         for (int t = 0; t < nt; t += 2) {
;             const bool last = (t == nt - 2);
;             const char* a1 = cA + (size_t)(t + 1) * kstep;
;             const char* a2 = last ? nA : cA + (size_t)(t + 2) * kstep; const char* b2 = last ? nB : cB + (size_t)(t + 2) * kstep;
;             const char* a3 = a2 + kstep; const char* b3 = b2 + kstep;
;             if (last && has_next) S.a_ready(nxt);
;             if constexpr (SP2) {
;             PG8_LDB(B0, 0, 0); PG8_LDB(B1, 0, 1); PG8_SCHED; PG8_LDA(At, 0, 0); PG8_STAGE(PG8_SA(1, 1), a1 + hstep, voffA);
;             PG8_WAIT_V(8); PG8_WAIT_L(0); PG8_BAR; PG8_MMA(0, 0, At, B0); PG8_MMA(0, 1, At, B1); PG8_BAR; PG8_SCHED;
;             PG8_LDA(At, 0, 1); PG8_STAGE(PG8_SB(0, 0), b2, voffB); PG8_STAGE(PG8_SB(0, 1), b2 + hstep, voffB); PG8_STAGE(PG8_SA(0, 0), a2, voffA);
.LBB0_734:
	s_add_u32 s26, s24, 0xfffc0080
	s_addc_u32 s27, s25, -1
	s_add_i32 s45, 0, 0x10000
	s_cmp_eq_u32 s50, 12
	s_cselect_b32 s29, s19, s27
	s_cselect_b32 s28, s54, s26
	s_cselect_b32 s27, s17, s59
	s_cselect_b32 s26, s55, s58
	s_add_i32 s68, 0, 0x14000
	v_add_u32_e32 v50, s45, v171
	v_add_u32_e32 v152, s68, v171
	ds_read_b128 v[26:29], v50
	ds_read_b128 v[30:33], v50 offset:1024
	ds_read_b128 v[46:49], v50 offset:2048
	ds_read_b128 v[50:53], v50 offset:3072
	ds_read_b128 v[162:165], v152
	ds_read_b128 v[166:169], v152 offset:1024
	ds_read_b128 v[176:179], v152 offset:2048
	ds_read_b128 v[180:183], v152 offset:3072
	v_lshl_add_u64 v[152:153], s[24:25], 0, v[148:149]
	s_add_i32 m0, s35, 0xc000
	ds_read_b128 v[184:187], v174
	ds_read_b128 v[188:191], v174 offset:1024
	ds_read_b128 v[192:195], v174 offset:2048
	ds_read_b128 v[196:199], v174 offset:3072
	ds_read_b128 v[200:203], v174 offset:4096
	ds_read_b128 v[210:213], v174 offset:5120
	ds_read_b128 v[214:217], v174 offset:6144
	ds_read_b128 v[218:221], v174 offset:7168
	global_load_lds_dwordx4 v[152:153], off
	v_lshl_add_u64 v[152:153], s[24:25], 0, v[150:151]
	s_add_i32 m0, s35, 0xe000
	s_nop 0
	global_load_lds_dwordx4 v[152:153], off
	s_waitcnt vmcnt(8) lgkmcnt(0)
	s_barrier
	s_setprio 1
	v_mfma_f32_16x16x32_bf16 v[142:145], v[26:29], v[184:187], v[142:145]
	v_mfma_f32_16x16x32_bf16 v[138:141], v[46:49], v[184:187], v[138:141]
	v_mfma_f32_16x16x32_bf16 v[126:129], v[26:29], v[192:195], v[126:129]
	v_mfma_f32_16x16x32_bf16 v[122:125], v[46:49], v[192:195], v[122:125]
	v_mfma_f32_16x16x32_bf16 v[110:113], v[26:29], v[200:203], v[110:113]
	v_mfma_f32_16x16x32_bf16 v[106:109], v[46:49], v[200:203], v[106:109]
	v_mfma_f32_16x16x32_bf16 v[94:97], v[26:29], v[214:217], v[94:97]
	v_mfma_f32_16x16x32_bf16 v[90:93], v[46:49], v[214:217], v[90:93]
	v_mfma_f32_16x16x32_bf16 v[142:145], v[30:33], v[188:191], v[142:145]
	v_mfma_f32_16x16x32_bf16 v[138:141], v[50:53], v[188:191], v[138:141]
	v_mfma_f32_16x16x32_bf16 v[126:129], v[30:33], v[196:199], v[126:129]
	v_mfma_f32_16x16x32_bf16 v[122:125], v[50:53], v[196:199], v[122:125]
	v_mfma_f32_16x16x32_bf16 v[110:113], v[30:33], v[210:213], v[110:113]
	v_mfma_f32_16x16x32_bf16 v[106:109], v[50:53], v[210:213], v[106:109]
	v_mfma_f32_16x16x32_bf16 v[94:97], v[30:33], v[218:221], v[94:97]
	v_mfma_f32_16x16x32_bf16 v[90:93], v[50:53], v[218:221], v[90:93]
	s_setprio 0
	s_setprio 1
	v_mfma_f32_16x16x32_bf16 v[134:137], v[162:165], v[184:187], v[134:137]
	v_mfma_f32_16x16x32_bf16 v[130:133], v[176:179], v[184:187], v[130:133]
	v_mfma_f32_16x16x32_bf16 v[118:121], v[162:165], v[192:195], v[118:121]
	v_mfma_f32_16x16x32_bf16 v[114:117], v[176:179], v[192:195], v[114:117]
	v_mfma_f32_16x16x32_bf16 v[102:105], v[162:165], v[200:203], v[102:105]
	v_mfma_f32_16x16x32_bf16 v[98:101], v[176:179], v[200:203], v[98:101]
	v_mfma_f32_16x16x32_bf16 v[86:89], v[162:165], v[214:217], v[86:89]
	v_mfma_f32_16x16x32_bf16 v[82:85], v[176:179], v[214:217], v[82:85]
	v_mfma_f32_16x16x32_bf16 v[134:137], v[166:169], v[188:191], v[134:137]
	v_mfma_f32_16x16x32_bf16 v[130:133], v[180:183], v[188:191], v[130:133]
	v_mfma_f32_16x16x32_bf16 v[118:121], v[166:169], v[196:199], v[118:121]
	v_mfma_f32_16x16x32_bf16 v[114:117], v[180:183], v[196:199], v[114:117]
	v_mfma_f32_16x16x32_bf16 v[102:105], v[166:169], v[210:213], v[102:105]
	v_mfma_f32_16x16x32_bf16 v[98:101], v[180:183], v[210:213], v[98:101]
	v_mfma_f32_16x16x32_bf16 v[86:89], v[166:169], v[218:221], v[86:89]
	v_mfma_f32_16x16x32_bf16 v[82:85], v[180:183], v[218:221], v[82:85]
	s_barrier
	s_setprio 0
	s_add_i32 s45, s45, s34
	v_lshl_add_u64 v[152:153], s[26:27], 0, v[0:1]
	s_mov_b32 m0, s45
	ds_read_b128 v[184:187], v174 offset:16384
	ds_read_b128 v[188:191], v174 offset:17408
	ds_read_b128 v[192:195], v174 offset:18432
	ds_read_b128 v[196:199], v174 offset:19456
	ds_read_b128 v[200:203], v174 offset:20480
	ds_read_b128 v[210:213], v174 offset:21504
	ds_read_b128 v[214:217], v174 offset:22528
	ds_read_b128 v[218:221], v174 offset:23552
	global_load_lds_dwordx4 v[152:153], off
	s_add_i32 m0, s45, 0x2000
	s_add_u32 s64, s26, 0x40000
	v_lshl_add_u64 v[222:223], s[26:27], 0, v[146:147]
	s_addc_u32 s65, s27, 0
	s_add_i32 s45, s68, s34
	global_load_lds_dwordx4 v[222:223], off
	v_lshl_add_u64 v[224:225], s[64:65], 0, v[0:1]
	s_mov_b32 m0, s45
	v_lshl_add_u64 v[226:227], s[28:29], 0, v[146:147]
	global_load_lds_dwordx4 v[224:225], off
	v_lshl_add_u64 v[224:225], s[64:65], 0, v[146:147]
	s_add_i32 m0, s45, 0x2000
	s_nop 0
	global_load_lds_dwordx4 v[224:225], off
	v_lshl_add_u64 v[224:225], s[28:29], 0, v[0:1]
	s_mov_b32 m0, s35
	s_nop 0
	global_load_lds_dwordx4 v[224:225], off
	s_mov_b32 m0, s36
	s_nop 0
	global_load_lds_dwordx4 v[226:227], off
	s_waitcnt vmcnt(8) lgkmcnt(0)
	s_barrier
; #define PG8_STAGE(bufoff, gbase, voff) do { _Pragma("unroll") for (int _i = 0; _i < 2; ++_i) \
;         __builtin_amdgcn_global_load_lds((const unsigned*)((const char*)(gbase) + (voff)[_i]), (PG8_LAS unsigned*)(lds + (bufoff) + ldsw + _i * 8192), 16, 0, 0); } while (0)
; #define PG8_LDA(dst, b, h) do { _Pragma("unroll") for (int m = 0; m < 4; ++m) _Pragma("unroll") for (int k = 0; k < 2; ++k) dst[m][k] = *(const PG8_LAS bf16x8*)(lds + PG8_SA(b, h) + aoff + m * 2048 + k * 1024); } while (0)
; #define PG8_LDB(dst, b, h) do { _Pragma("unroll") for (int n = 0; n < 2; ++n) _Pragma("unroll") for (int k = 0; k < 2; ++k) dst[n][k] = *(const PG8_LAS bf16x8*)(lds + PG8_SB(b, h) + boff + n * 2048 + k * 1024); } while (0)
; #define PG8_MMA(ai, bj, At, Bt) do { __builtin_amdgcn_s_setprio(1); _Pragma("unroll") for (int m = 0; m < 4; ++m) _Pragma("unroll") for (int n = 0; n < 2; ++n) _Pragma("unroll") for (int k = 0; k < 2; ++k) \
;         acc[ai][bj][m][n] = __builtin_amdgcn_mfma_f32_16x16x32_bf16(Bt[n][k], At[m][k], acc[ai][bj][m][n], 0, 0, 0); __builtin_amdgcn_s_setprio(0); } while (0)
; #define PG8_WAIT_V(n) asm volatile("s_waitcnt vmcnt(" #n ")" ::: "memory")
; #define PG8_WAIT_L(n) asm volatile("s_waitcnt lgkmcnt(" #n ")" ::: "memory")
; #define PG8_BAR __builtin_amdgcn_s_barrier()
; #define PG8_SCHED __builtin_amdgcn_sched_barrier(0)
; template <class Epi, class Sched, bool ALIGN_EPI = false, bool SP2 = false>
; __device__ __forceinline__ void gemm_phase(PG8_LAS unsigned char* lds, const Gemm g, const Sched& S, const Epi& E, const int wave_s) {
;     ...
;             PG8_WAIT_V(8); PG8_WAIT_L(0); PG8_BAR; PG8_MMA(1, 0, At, B0); PG8_MMA(1, 1, At, B1); PG8_BAR; PG8_SCHED;
;             PG8_LDB(B0, 1, 0); PG8_LDB(B1, 1, 1); PG8_SCHED; PG8_LDA(At, 1, 0); PG8_STAGE(PG8_SA(0, 1), a2 + hstep, voffA);
;             PG8_WAIT_V(8); PG8_WAIT_L(0); PG8_BAR; PG8_MMA(0, 0, At, B0); PG8_MMA(0, 1, At, B1); PG8_BAR; PG8_SCHED;
	s_setprio 1
	v_mfma_f32_16x16x32_bf16 v[78:81], v[26:29], v[184:187], v[78:81]
	v_mfma_f32_16x16x32_bf16 v[74:77], v[46:49], v[184:187], v[74:77]
	v_mfma_f32_16x16x32_bf16 v[62:65], v[26:29], v[192:195], v[62:65]
	v_mfma_f32_16x16x32_bf16 v[58:61], v[46:49], v[192:195], v[58:61]
	v_mfma_f32_16x16x32_bf16 v[38:41], v[26:29], v[200:203], v[38:41]
	v_mfma_f32_16x16x32_bf16 v[34:37], v[46:49], v[200:203], v[34:37]
	v_mfma_f32_16x16x32_bf16 v[14:17], v[26:29], v[214:217], v[14:17]
	v_mfma_f32_16x16x32_bf16 v[10:13], v[46:49], v[214:217], v[10:13]
	v_mfma_f32_16x16x32_bf16 v[78:81], v[30:33], v[188:191], v[78:81]
	v_mfma_f32_16x16x32_bf16 v[74:77], v[50:53], v[188:191], v[74:77]
	v_mfma_f32_16x16x32_bf16 v[62:65], v[30:33], v[196:199], v[62:65]
	v_mfma_f32_16x16x32_bf16 v[58:61], v[50:53], v[196:199], v[58:61]
	v_mfma_f32_16x16x32_bf16 v[38:41], v[30:33], v[210:213], v[38:41]
	v_mfma_f32_16x16x32_bf16 v[34:37], v[50:53], v[210:213], v[34:37]
	v_mfma_f32_16x16x32_bf16 v[14:17], v[30:33], v[218:221], v[14:17]
	v_mfma_f32_16x16x32_bf16 v[10:13], v[50:53], v[218:221], v[10:13]
	s_setprio 0
	s_setprio 1
	v_mfma_f32_16x16x32_bf16 v[42:45], v[176:179], v[192:195], v[42:45]
	v_mfma_f32_16x16x32_bf16 v[22:25], v[162:165], v[200:203], v[22:25]
	v_mfma_f32_16x16x32_bf16 v[18:21], v[176:179], v[200:203], v[18:21]
	v_mfma_f32_16x16x32_bf16 v[6:9], v[162:165], v[214:217], v[6:9]
	v_mfma_f32_16x16x32_bf16 v[2:5], v[176:179], v[214:217], v[2:5]
	v_mfma_f32_16x16x32_bf16 v[26:29], v[162:165], v[184:187], v[70:73]
	v_mfma_f32_16x16x32_bf16 v[30:33], v[176:179], v[184:187], v[66:69]
	v_mfma_f32_16x16x32_bf16 v[46:49], v[162:165], v[192:195], v[54:57]
	v_mfma_f32_16x16x32_bf16 v[42:45], v[180:183], v[196:199], v[42:45]
	v_mfma_f32_16x16x32_bf16 v[22:25], v[166:169], v[210:213], v[22:25]
	v_mfma_f32_16x16x32_bf16 v[18:21], v[180:183], v[210:213], v[18:21]
	v_mfma_f32_16x16x32_bf16 v[6:9], v[166:169], v[218:221], v[6:9]
	v_mfma_f32_16x16x32_bf16 v[2:5], v[180:183], v[218:221], v[2:5]
	v_mfma_f32_16x16x32_bf16 v[26:29], v[166:169], v[188:191], v[26:29]
	v_mfma_f32_16x16x32_bf16 v[30:33], v[180:183], v[188:191], v[30:33]
	v_mfma_f32_16x16x32_bf16 v[46:49], v[166:169], v[196:199], v[46:49]
	s_barrier
	s_setprio 0
	s_add_i32 s45, 0, 0x18000
	s_add_i32 s64, 0, 0x1c000
	v_add_u32_e32 v70, s45, v171
	v_add_u32_e32 v175, s64, v171
	ds_read_b128 v[50:53], v70
	ds_read_b128 v[54:57], v70 offset:1024
	ds_read_b128 v[66:69], v70 offset:2048
	ds_read_b128 v[70:73], v70 offset:3072
	ds_read_b128 v[162:165], v175
	ds_read_b128 v[166:169], v175 offset:1024
	ds_read_b128 v[176:179], v175 offset:2048
	ds_read_b128 v[180:183], v175 offset:3072
	s_add_u32 s28, s28, 0x40000
	s_addc_u32 s29, s29, 0
	s_mov_b32 m0, s37
	v_lshl_add_u64 v[228:229], s[28:29], 0, v[0:1]
	ds_read_b128 v[184:187], v174 offset:32768
	ds_read_b128 v[188:191], v174 offset:33792
	ds_read_b128 v[192:195], v174 offset:34816
	ds_read_b128 v[196:199], v174 offset:35840
	ds_read_b128 v[200:203], v174 offset:36864
	ds_read_b128 v[210:213], v174 offset:37888
	ds_read_b128 v[214:217], v174 offset:38912
	ds_read_b128 v[218:221], v174 offset:39936
	global_load_lds_dwordx4 v[228:229], off
	v_lshl_add_u64 v[228:229], s[28:29], 0, v[146:147]
	s_mov_b32 m0, s38
	s_nop 0
	global_load_lds_dwordx4 v[228:229], off
	s_waitcnt vmcnt(8) lgkmcnt(0)
	s_barrier
	s_setprio 1
	v_mfma_f32_16x16x32_bf16 v[142:145], v[50:53], v[184:187], v[142:145]
	v_mfma_f32_16x16x32_bf16 v[138:141], v[66:69], v[184:187], v[138:141]
	v_mfma_f32_16x16x32_bf16 v[126:129], v[50:53], v[192:195], v[126:129]
	v_mfma_f32_16x16x32_bf16 v[122:125], v[66:69], v[192:195], v[122:125]
	v_mfma_f32_16x16x32_bf16 v[110:113], v[50:53], v[200:203], v[110:113]
	v_mfma_f32_16x16x32_bf16 v[106:109], v[66:69], v[200:203], v[106:109]
	v_mfma_f32_16x16x32_bf16 v[94:97], v[50:53], v[214:217], v[94:97]
	v_mfma_f32_16x16x32_bf16 v[90:93], v[66:69], v[214:217], v[90:93]
	v_mfma_f32_16x16x32_bf16 v[142:145], v[54:57], v[188:191], v[142:145]
	v_mfma_f32_16x16x32_bf16 v[138:141], v[70:73], v[188:191], v[138:141]
	v_mfma_f32_16x16x32_bf16 v[126:129], v[54:57], v[196:199], v[126:129]
	v_mfma_f32_16x16x32_bf16 v[122:125], v[70:73], v[196:199], v[122:125]
	v_mfma_f32_16x16x32_bf16 v[110:113], v[54:57], v[210:213], v[110:113]
	v_mfma_f32_16x16x32_bf16 v[106:109], v[70:73], v[210:213], v[106:109]
	v_mfma_f32_16x16x32_bf16 v[94:97], v[54:57], v[218:221], v[94:97]
	v_mfma_f32_16x16x32_bf16 v[90:93], v[70:73], v[218:221], v[90:93]
	s_setprio 0
	s_setprio 1
	v_mfma_f32_16x16x32_bf16 v[134:137], v[162:165], v[184:187], v[134:137]
	v_mfma_f32_16x16x32_bf16 v[130:133], v[176:179], v[184:187], v[130:133]
	v_mfma_f32_16x16x32_bf16 v[118:121], v[162:165], v[192:195], v[118:121]
	v_mfma_f32_16x16x32_bf16 v[114:117], v[176:179], v[192:195], v[114:117]
	v_mfma_f32_16x16x32_bf16 v[102:105], v[162:165], v[200:203], v[102:105]
	v_mfma_f32_16x16x32_bf16 v[98:101], v[176:179], v[200:203], v[98:101]
	v_mfma_f32_16x16x32_bf16 v[86:89], v[162:165], v[214:217], v[86:89]
	v_mfma_f32_16x16x32_bf16 v[82:85], v[176:179], v[214:217], v[82:85]
	v_mfma_f32_16x16x32_bf16 v[134:137], v[166:169], v[188:191], v[134:137]
	v_mfma_f32_16x16x32_bf16 v[130:133], v[180:183], v[188:191], v[130:133]
	v_mfma_f32_16x16x32_bf16 v[118:121], v[166:169], v[196:199], v[118:121]
	v_mfma_f32_16x16x32_bf16 v[114:117], v[180:183], v[196:199], v[114:117]
	v_mfma_f32_16x16x32_bf16 v[102:105], v[166:169], v[210:213], v[102:105]
	v_mfma_f32_16x16x32_bf16 v[98:101], v[180:183], v[210:213], v[98:101]
	v_mfma_f32_16x16x32_bf16 v[86:89], v[166:169], v[218:221], v[86:89]
	v_mfma_f32_16x16x32_bf16 v[82:85], v[180:183], v[218:221], v[82:85]
	s_barrier
; #define PG8_STAGE(bufoff, gbase, voff) do { _Pragma("unroll") for (int _i = 0; _i < 2; ++_i) \
;         __builtin_amdgcn_global_load_lds((const unsigned*)((const char*)(gbase) + (voff)[_i]), (PG8_LAS unsigned*)(lds + (bufoff) + ldsw + _i * 8192), 16, 0, 0); } while (0)
; #define PG8_LDA(dst, b, h) do { _Pragma("unroll") for (int m = 0; m < 4; ++m) _Pragma("unroll") for (int k = 0; k < 2; ++k) dst[m][k] = *(const PG8_LAS bf16x8*)(lds + PG8_SA(b, h) + aoff + m * 2048 + k * 1024); } while (0)
; #define PG8_MMA(ai, bj, At, Bt) do { __builtin_amdgcn_s_setprio(1); _Pragma("unroll") for (int m = 0; m < 4; ++m) _Pragma("unroll") for (int n = 0; n < 2; ++n) _Pragma("unroll") for (int k = 0; k < 2; ++k) \
;         acc[ai][bj][m][n] = __builtin_amdgcn_mfma_f32_16x16x32_bf16(Bt[n][k], At[m][k], acc[ai][bj][m][n], 0, 0, 0); __builtin_amdgcn_s_setprio(0); } while (0)
; #define PG8_WAIT_V(n) asm volatile("s_waitcnt vmcnt(" #n ")" ::: "memory")
; #define PG8_WAIT_L(n) asm volatile("s_waitcnt lgkmcnt(" #n ")" ::: "memory")
; #define PG8_BAR __builtin_amdgcn_s_barrier()
; #define PG8_SCHED __builtin_amdgcn_sched_barrier(0)
; template <class Epi, class Sched, bool ALIGN_EPI = false, bool SP2 = false>
; __device__ __forceinline__ void gemm_phase(PG8_LAS unsigned char* lds, const Gemm g, const Sched& S, const Epi& E, const int wave_s) {
;     ...
;             PG8_LDA(At, 1, 1); PG8_STAGE(PG8_SB(1, 0), b3, voffB); PG8_STAGE(PG8_SB(1, 1), b3 + hstep, voffB); PG8_STAGE(PG8_SA(1, 0), a3, voffA);
;             PG8_WAIT_V(8); PG8_WAIT_L(0); PG8_BAR; PG8_MMA(1, 0, At, B0); PG8_MMA(1, 1, At, B1); PG8_BAR; PG8_SCHED;
;     ...
;         if constexpr (ALIGN_EPI) { if (wr == 0) PG8_BAR; }
	s_setprio 0
	s_add_i32 s28, s45, s34
	v_lshl_add_u64 v[152:153], v[152:153], 0, s[70:71]
	s_mov_b32 m0, s28
	ds_read_b128 v[184:187], v174 offset:49152
	ds_read_b128 v[188:191], v174 offset:50176
	ds_read_b128 v[192:195], v174 offset:51200
	ds_read_b128 v[196:199], v174 offset:52224
	ds_read_b128 v[200:203], v174 offset:53248
	ds_read_b128 v[210:213], v174 offset:54272
	ds_read_b128 v[214:217], v174 offset:55296
	ds_read_b128 v[218:221], v174 offset:56320
	global_load_lds_dwordx4 v[152:153], off
	s_add_i32 m0, s28, 0x2000
	s_add_u32 s26, s26, 0x40080
	v_lshl_add_u64 v[152:153], v[222:223], 0, s[70:71]
	s_addc_u32 s27, s27, 0
	s_add_i32 s28, s64, s34
	global_load_lds_dwordx4 v[152:153], off
	v_lshl_add_u64 v[152:153], s[26:27], 0, v[0:1]
	s_mov_b32 m0, s28
	s_nop 0
	global_load_lds_dwordx4 v[152:153], off
	v_lshl_add_u64 v[152:153], s[26:27], 0, v[146:147]
	s_add_i32 m0, s28, 0x2000
	s_nop 0
	global_load_lds_dwordx4 v[152:153], off
	v_lshl_add_u64 v[152:153], v[224:225], 0, s[70:71]
	s_mov_b32 m0, s40
	s_nop 0
	global_load_lds_dwordx4 v[152:153], off
	v_lshl_add_u64 v[152:153], v[226:227], 0, s[70:71]
	s_mov_b32 m0, s41
	s_nop 0
	global_load_lds_dwordx4 v[152:153], off
	s_waitcnt vmcnt(8) lgkmcnt(0)
	s_barrier
	s_setprio 1
	v_mfma_f32_16x16x32_bf16 v[78:81], v[50:53], v[184:187], v[78:81]
	v_mfma_f32_16x16x32_bf16 v[74:77], v[66:69], v[184:187], v[74:77]
	v_mfma_f32_16x16x32_bf16 v[62:65], v[50:53], v[192:195], v[62:65]
	v_mfma_f32_16x16x32_bf16 v[58:61], v[66:69], v[192:195], v[58:61]
	v_mfma_f32_16x16x32_bf16 v[38:41], v[50:53], v[200:203], v[38:41]
	v_mfma_f32_16x16x32_bf16 v[34:37], v[66:69], v[200:203], v[34:37]
	v_mfma_f32_16x16x32_bf16 v[14:17], v[50:53], v[214:217], v[14:17]
	v_mfma_f32_16x16x32_bf16 v[10:13], v[66:69], v[214:217], v[10:13]
	v_mfma_f32_16x16x32_bf16 v[78:81], v[54:57], v[188:191], v[78:81]
	v_mfma_f32_16x16x32_bf16 v[74:77], v[70:73], v[188:191], v[74:77]
	v_mfma_f32_16x16x32_bf16 v[62:65], v[54:57], v[196:199], v[62:65]
	v_mfma_f32_16x16x32_bf16 v[58:61], v[70:73], v[196:199], v[58:61]
	v_mfma_f32_16x16x32_bf16 v[38:41], v[54:57], v[210:213], v[38:41]
	v_mfma_f32_16x16x32_bf16 v[34:37], v[70:73], v[210:213], v[34:37]
	v_mfma_f32_16x16x32_bf16 v[14:17], v[54:57], v[218:221], v[14:17]
	v_mfma_f32_16x16x32_bf16 v[10:13], v[70:73], v[218:221], v[10:13]
	s_setprio 0
	s_setprio 1
	v_mfma_f32_16x16x32_bf16 v[26:29], v[162:165], v[184:187], v[26:29]
	v_mfma_f32_16x16x32_bf16 v[70:73], v[166:169], v[188:191], v[26:29]
	v_mfma_f32_16x16x32_bf16 v[26:29], v[176:179], v[184:187], v[30:33]
	v_mfma_f32_16x16x32_bf16 v[66:69], v[180:183], v[188:191], v[26:29]
	v_mfma_f32_16x16x32_bf16 v[26:29], v[162:165], v[192:195], v[46:49]
	v_mfma_f32_16x16x32_bf16 v[54:57], v[166:169], v[196:199], v[26:29]
	v_mfma_f32_16x16x32_bf16 v[26:29], v[176:179], v[192:195], v[42:45]
	v_mfma_f32_16x16x32_bf16 v[22:25], v[162:165], v[200:203], v[22:25]
	v_mfma_f32_16x16x32_bf16 v[18:21], v[176:179], v[200:203], v[18:21]
	v_mfma_f32_16x16x32_bf16 v[6:9], v[162:165], v[214:217], v[6:9]
	v_mfma_f32_16x16x32_bf16 v[2:5], v[176:179], v[214:217], v[2:5]
	v_mfma_f32_16x16x32_bf16 v[42:45], v[180:183], v[196:199], v[26:29]
	v_mfma_f32_16x16x32_bf16 v[22:25], v[166:169], v[210:213], v[22:25]
	v_mfma_f32_16x16x32_bf16 v[18:21], v[180:183], v[210:213], v[18:21]
	v_mfma_f32_16x16x32_bf16 v[6:9], v[166:169], v[218:221], v[6:9]
	v_mfma_f32_16x16x32_bf16 v[2:5], v[180:183], v[218:221], v[2:5]
	s_barrier
	s_setprio 0
	s_add_i32 s50, s50, 2
	s_add_u32 s24, s24, 0x100
	s_addc_u32 s25, s25, 0
	s_add_u32 s58, s58, 0x100
	s_addc_u32 s59, s59, 0
	s_cmp_gt_u32 s50, 13
	s_cbranch_scc0 .LBB0_734
	s_and_b64 vcc, exec, s[14:15]
	s_cbranch_vccz .LBB0_737
	s_barrier

; #define PG8_STAGE(bufoff, gbase, voff) do { _Pragma("unroll") for (int _i = 0; _i < 2; ++_i) \
;         __builtin_amdgcn_global_load_lds((const unsigned*)((const char*)(gbase) + (voff)[_i]), (PG8_LAS unsigned*)(lds + (bufoff) + ldsw + _i * 8192), 16, 0, 0); } while (0)
; #define PG8_LDA(dst, b, h) do { _Pragma("unroll") for (int m = 0; m < 4; ++m) _Pragma("unroll") for (int k = 0; k < 2; ++k) dst[m][k] = *(const PG8_LAS bf16x8*)(lds + PG8_SA(b, h) + aoff + m * 2048 + k * 1024); } while (0)
; #define PG8_LDB(dst, b, h) do { _Pragma("unroll") for (int n = 0; n < 2; ++n) _Pragma("unroll") for (int k = 0; k < 2; ++k) dst[n][k] = *(const PG8_LAS bf16x8*)(lds + PG8_SB(b, h) + boff + n * 2048 + k * 1024); } while (0)
; #define PG8_MMA(ai, bj, At, Bt) do { __builtin_amdgcn_s_setprio(1); _Pragma("unroll") for (int m = 0; m < 4; ++m) _Pragma("unroll") for (int n = 0; n < 2; ++n) _Pragma("unroll") for (int k = 0; k < 2; ++k) \
;         acc[ai][bj][m][n] = __builtin_amdgcn_mfma_f32_16x16x32_bf16(Bt[n][k], At[m][k], acc[ai][bj][m][n], 0, 0, 0); __builtin_amdgcn_s_setprio(0); } while (0)
; #define PG8_WAIT_V(n) asm volatile("s_waitcnt vmcnt(" #n ")" ::: "memory")
; #define PG8_WAIT_L(n) asm volatile("s_waitcnt lgkmcnt(" #n ")" ::: "memory")
; #define PG8_BAR __builtin_amdgcn_s_barrier()
; template <class Epi, class Sched, bool ALIGN_EPI = false, bool SP2 = false>
; __device__ __forceinline__ void gemm_phase(PG8_LAS unsigned char* lds, const Gemm g, const Sched& S, const Epi& E, const int wave_s) {
;     ...
;         for (int t = 0; t < nt; t += 2) {
;             const bool last = (t == nt - 2);
;             const char* a1 = cA + (size_t)(t + 1) * kstep;
;             const char* a2 = last ? nA : cA + (size_t)(t + 2) * kstep; const char* b2 = last ? nB : cB + (size_t)(t + 2) * kstep;
;             const char* a3 = a2 + kstep; const char* b3 = b2 + kstep;
;             if (last && has_next) S.a_ready(nxt);
;             if constexpr (SP2) {
;             PG8_LDB(B0, 0, 0); PG8_LDB(B1, 0, 1); PG8_SCHED; PG8_LDA(At, 0, 0); PG8_STAGE(PG8_SA(1, 1), a1 + hstep, voffA);
;             PG8_WAIT_V(8); PG8_WAIT_L(0); PG8_BAR; PG8_MMA(0, 0, At, B0); PG8_MMA(0, 1, At, B1); PG8_BAR; PG8_SCHED;
;             PG8_LDA(At, 0, 1); PG8_STAGE(PG8_SB(0, 0), b2, voffB); PG8_STAGE(PG8_SB(0, 1), b2 + hstep, voffB); PG8_STAGE(PG8_SA(0, 0), a2, voffA);
.LBB0_806:
	s_add_u32 s8, s10, 0x100
	s_addc_u32 s9, s11, 0
	s_add_i32 s45, 0, 0x10000
	s_cmp_eq_u32 s75, 40
	s_cselect_b32 s49, s37, s9
	s_cselect_b32 s48, s36, s8
	v_add_u32_e32 v0, s45, v203
	s_cselect_b32 s41, s39, vcc_hi
	s_cselect_b32 s40, s38, vcc_lo
	s_add_i32 s80, 0, 0x14000
	ds_read_b128 v[122:125], v0
	ds_read_b128 v[126:129], v0 offset:1024
	ds_read_b128 v[138:141], v0 offset:2048
	ds_read_b128 v[142:145], v0 offset:3072
	v_add_u32_e32 v0, s80, v203
	ds_read_b128 v[146:149], v0
	ds_read_b128 v[150:153], v0 offset:1024
	ds_read_b128 v[174:177], v0 offset:2048
	ds_read_b128 v[178:181], v0 offset:3072
	v_lshl_add_u64 v[226:227], s[10:11], 0, v[170:171]
	s_add_i32 m0, s76, 0xc000
	ds_read_b128 v[182:185], v212
	ds_read_b128 v[186:189], v212 offset:1024
	ds_read_b128 v[190:193], v212 offset:2048
	ds_read_b128 v[194:197], v212 offset:3072
	ds_read_b128 v[198:201], v212 offset:4096
	ds_read_b128 v[214:217], v212 offset:5120
	ds_read_b128 v[218:221], v212 offset:6144
	ds_read_b128 v[222:225], v212 offset:7168
	global_load_lds_dwordx4 v[226:227], off
	v_lshl_add_u64 v[226:227], s[10:11], 0, v[172:173]
	s_add_i32 m0, s76, 0xe000
	s_nop 0
	global_load_lds_dwordx4 v[226:227], off
	s_waitcnt vmcnt(8) lgkmcnt(0)
	s_barrier
	s_setprio 1
	v_mfma_f32_16x16x32_bf16 v[6:9], v[122:125], v[182:185], v[6:9]
	v_mfma_f32_16x16x32_bf16 v[2:5], v[138:141], v[182:185], v[2:5]
	v_mfma_f32_16x16x32_bf16 v[134:137], v[122:125], v[190:193], v[134:137]
	v_mfma_f32_16x16x32_bf16 v[130:133], v[138:141], v[190:193], v[130:133]
	v_mfma_f32_16x16x32_bf16 v[118:121], v[122:125], v[198:201], v[118:121]
	v_mfma_f32_16x16x32_bf16 v[114:117], v[138:141], v[198:201], v[114:117]
	v_mfma_f32_16x16x32_bf16 v[110:113], v[122:125], v[218:221], v[110:113]
	v_mfma_f32_16x16x32_bf16 v[106:109], v[138:141], v[218:221], v[106:109]
	v_mfma_f32_16x16x32_bf16 v[6:9], v[126:129], v[186:189], v[6:9]
	v_mfma_f32_16x16x32_bf16 v[2:5], v[142:145], v[186:189], v[2:5]
	v_mfma_f32_16x16x32_bf16 v[134:137], v[126:129], v[194:197], v[134:137]
	v_mfma_f32_16x16x32_bf16 v[130:133], v[142:145], v[194:197], v[130:133]
	v_mfma_f32_16x16x32_bf16 v[118:121], v[126:129], v[214:217], v[118:121]
	v_mfma_f32_16x16x32_bf16 v[114:117], v[142:145], v[214:217], v[114:117]
	v_mfma_f32_16x16x32_bf16 v[110:113], v[126:129], v[222:225], v[110:113]
	v_mfma_f32_16x16x32_bf16 v[106:109], v[142:145], v[222:225], v[106:109]
	s_setprio 0
	s_setprio 1
	v_mfma_f32_16x16x32_bf16 v[70:73], v[146:149], v[182:185], v[70:73]
	v_mfma_f32_16x16x32_bf16 v[66:69], v[174:177], v[182:185], v[66:69]
	v_mfma_f32_16x16x32_bf16 v[62:65], v[146:149], v[190:193], v[62:65]
	v_mfma_f32_16x16x32_bf16 v[58:61], v[174:177], v[190:193], v[58:61]
	v_mfma_f32_16x16x32_bf16 v[54:57], v[146:149], v[198:201], v[54:57]
	v_mfma_f32_16x16x32_bf16 v[50:53], v[174:177], v[198:201], v[50:53]
	v_mfma_f32_16x16x32_bf16 v[46:49], v[146:149], v[218:221], v[46:49]
	v_mfma_f32_16x16x32_bf16 v[42:45], v[174:177], v[218:221], v[42:45]
	v_mfma_f32_16x16x32_bf16 v[70:73], v[150:153], v[186:189], v[70:73]
	v_mfma_f32_16x16x32_bf16 v[66:69], v[178:181], v[186:189], v[66:69]
	v_mfma_f32_16x16x32_bf16 v[62:65], v[150:153], v[194:197], v[62:65]
	v_mfma_f32_16x16x32_bf16 v[58:61], v[178:181], v[194:197], v[58:61]
	v_mfma_f32_16x16x32_bf16 v[54:57], v[150:153], v[214:217], v[54:57]
	v_mfma_f32_16x16x32_bf16 v[50:53], v[178:181], v[214:217], v[50:53]
	v_mfma_f32_16x16x32_bf16 v[46:49], v[150:153], v[222:225], v[46:49]
	v_mfma_f32_16x16x32_bf16 v[42:45], v[178:181], v[222:225], v[42:45]
	s_barrier
	s_setprio 0
	s_add_i32 s10, s45, s44
	v_lshl_add_u64 v[226:227], s[40:41], 0, v[166:167]
	s_mov_b32 m0, s10
	ds_read_b128 v[182:185], v212 offset:16384
	ds_read_b128 v[186:189], v212 offset:17408
	ds_read_b128 v[190:193], v212 offset:18432
	ds_read_b128 v[194:197], v212 offset:19456
	ds_read_b128 v[198:201], v212 offset:20480
	ds_read_b128 v[214:217], v212 offset:21504
	ds_read_b128 v[218:221], v212 offset:22528
	ds_read_b128 v[222:225], v212 offset:23552
	global_load_lds_dwordx4 v[226:227], off
	s_add_i32 m0, s10, 0x2000
	s_add_u32 s10, s40, 0xb0000
	v_lshl_add_u64 v[228:229], s[40:41], 0, v[162:163]
	s_addc_u32 s11, s41, 0
	s_add_i32 s45, s80, s44
	global_load_lds_dwordx4 v[228:229], off
	v_lshl_add_u64 v[230:231], s[10:11], 0, v[166:167]
	s_mov_b32 m0, s45
	v_lshl_add_u64 v[232:233], s[48:49], 0, v[164:165]
	global_load_lds_dwordx4 v[230:231], off
	v_lshl_add_u64 v[230:231], s[10:11], 0, v[162:163]
	s_add_i32 m0, s45, 0x2000
	s_nop 0
	global_load_lds_dwordx4 v[230:231], off
	v_lshl_add_u64 v[230:231], s[48:49], 0, v[168:169]
	s_mov_b32 m0, s76
	s_nop 0
	global_load_lds_dwordx4 v[230:231], off
	s_mov_b32 m0, s77
	s_nop 0
	global_load_lds_dwordx4 v[232:233], off
	s_waitcnt vmcnt(8) lgkmcnt(0)
	s_barrier
; #define PG8_STAGE(bufoff, gbase, voff) do { _Pragma("unroll") for (int _i = 0; _i < 2; ++_i) \
;         __builtin_amdgcn_global_load_lds((const unsigned*)((const char*)(gbase) + (voff)[_i]), (PG8_LAS unsigned*)(lds + (bufoff) + ldsw + _i * 8192), 16, 0, 0); } while (0)
; #define PG8_LDA(dst, b, h) do { _Pragma("unroll") for (int m = 0; m < 4; ++m) _Pragma("unroll") for (int k = 0; k < 2; ++k) dst[m][k] = *(const PG8_LAS bf16x8*)(lds + PG8_SA(b, h) + aoff + m * 2048 + k * 1024); } while (0)
; #define PG8_LDB(dst, b, h) do { _Pragma("unroll") for (int n = 0; n < 2; ++n) _Pragma("unroll") for (int k = 0; k < 2; ++k) dst[n][k] = *(const PG8_LAS bf16x8*)(lds + PG8_SB(b, h) + boff + n * 2048 + k * 1024); } while (0)
; #define PG8_MMA(ai, bj, At, Bt) do { __builtin_amdgcn_s_setprio(1); _Pragma("unroll") for (int m = 0; m < 4; ++m) _Pragma("unroll") for (int n = 0; n < 2; ++n) _Pragma("unroll") for (int k = 0; k < 2; ++k) \
;         acc[ai][bj][m][n] = __builtin_amdgcn_mfma_f32_16x16x32_bf16(Bt[n][k], At[m][k], acc[ai][bj][m][n], 0, 0, 0); __builtin_amdgcn_s_setprio(0); } while (0)
; #define PG8_WAIT_V(n) asm volatile("s_waitcnt vmcnt(" #n ")" ::: "memory")
; #define PG8_WAIT_L(n) asm volatile("s_waitcnt lgkmcnt(" #n ")" ::: "memory")
; #define PG8_BAR __builtin_amdgcn_s_barrier()
; #define PG8_SCHED __builtin_amdgcn_sched_barrier(0)
; template <class Epi, class Sched, bool ALIGN_EPI = false, bool SP2 = false>
; __device__ __forceinline__ void gemm_phase(PG8_LAS unsigned char* lds, const Gemm g, const Sched& S, const Epi& E, const int wave_s) {
;     ...
;             PG8_WAIT_V(8); PG8_WAIT_L(0); PG8_BAR; PG8_MMA(1, 0, At, B0); PG8_MMA(1, 1, At, B1); PG8_BAR; PG8_SCHED;
;             PG8_LDB(B0, 1, 0); PG8_LDB(B1, 1, 1); PG8_SCHED; PG8_LDA(At, 1, 0); PG8_STAGE(PG8_SA(0, 1), a2 + hstep, voffA);
;             PG8_WAIT_V(8); PG8_WAIT_L(0); PG8_BAR; PG8_MMA(0, 0, At, B0); PG8_MMA(0, 1, At, B1); PG8_BAR; PG8_SCHED;
	s_setprio 1
	v_mfma_f32_16x16x32_bf16 v[102:105], v[122:125], v[182:185], v[102:105]
	v_mfma_f32_16x16x32_bf16 v[98:101], v[138:141], v[182:185], v[98:101]
	v_mfma_f32_16x16x32_bf16 v[94:97], v[122:125], v[190:193], v[94:97]
	v_mfma_f32_16x16x32_bf16 v[90:93], v[138:141], v[190:193], v[90:93]
	v_mfma_f32_16x16x32_bf16 v[86:89], v[122:125], v[198:201], v[86:89]
	v_mfma_f32_16x16x32_bf16 v[82:85], v[138:141], v[198:201], v[82:85]
	v_mfma_f32_16x16x32_bf16 v[78:81], v[122:125], v[218:221], v[78:81]
	v_mfma_f32_16x16x32_bf16 v[74:77], v[138:141], v[218:221], v[74:77]
	v_mfma_f32_16x16x32_bf16 v[102:105], v[126:129], v[186:189], v[102:105]
	v_mfma_f32_16x16x32_bf16 v[98:101], v[142:145], v[186:189], v[98:101]
	v_mfma_f32_16x16x32_bf16 v[94:97], v[126:129], v[194:197], v[94:97]
	v_mfma_f32_16x16x32_bf16 v[90:93], v[142:145], v[194:197], v[90:93]
	v_mfma_f32_16x16x32_bf16 v[86:89], v[126:129], v[214:217], v[86:89]
	v_mfma_f32_16x16x32_bf16 v[82:85], v[142:145], v[214:217], v[82:85]
	v_mfma_f32_16x16x32_bf16 v[78:81], v[126:129], v[222:225], v[78:81]
	v_mfma_f32_16x16x32_bf16 v[74:77], v[142:145], v[222:225], v[74:77]
	s_setprio 0
	s_setprio 1
	v_mfma_f32_16x16x32_bf16 v[38:41], v[146:149], v[182:185], v[38:41]
	v_mfma_f32_16x16x32_bf16 v[34:37], v[174:177], v[182:185], v[34:37]
	v_mfma_f32_16x16x32_bf16 v[30:33], v[146:149], v[190:193], v[30:33]
	v_mfma_f32_16x16x32_bf16 v[26:29], v[174:177], v[190:193], v[26:29]
	v_mfma_f32_16x16x32_bf16 v[22:25], v[146:149], v[198:201], v[22:25]
	v_mfma_f32_16x16x32_bf16 v[18:21], v[174:177], v[198:201], v[18:21]
	v_mfma_f32_16x16x32_bf16 v[14:17], v[146:149], v[218:221], v[14:17]
	v_mfma_f32_16x16x32_bf16 v[10:13], v[174:177], v[218:221], v[10:13]
	v_mfma_f32_16x16x32_bf16 v[38:41], v[150:153], v[186:189], v[38:41]
	v_mfma_f32_16x16x32_bf16 v[34:37], v[178:181], v[186:189], v[34:37]
	v_mfma_f32_16x16x32_bf16 v[30:33], v[150:153], v[194:197], v[30:33]
	v_mfma_f32_16x16x32_bf16 v[26:29], v[178:181], v[194:197], v[26:29]
	v_mfma_f32_16x16x32_bf16 v[22:25], v[150:153], v[214:217], v[22:25]
	v_mfma_f32_16x16x32_bf16 v[18:21], v[178:181], v[214:217], v[18:21]
	v_mfma_f32_16x16x32_bf16 v[14:17], v[150:153], v[222:225], v[14:17]
	v_mfma_f32_16x16x32_bf16 v[10:13], v[178:181], v[222:225], v[10:13]
	s_barrier
	s_setprio 0
	s_add_i32 s45, 0, 0x18000
	v_add_u32_e32 v0, s45, v203
	s_add_i32 s80, 0, 0x1c000
	ds_read_b128 v[122:125], v0
	ds_read_b128 v[126:129], v0 offset:1024
	ds_read_b128 v[138:141], v0 offset:2048
	ds_read_b128 v[142:145], v0 offset:3072
	v_add_u32_e32 v0, s80, v203
	ds_read_b128 v[146:149], v0
	ds_read_b128 v[150:153], v0 offset:1024
	ds_read_b128 v[174:177], v0 offset:2048
	ds_read_b128 v[178:181], v0 offset:3072
	s_add_u32 s10, s48, 0xb0000
	s_addc_u32 s11, s49, 0
	s_mov_b32 m0, s88
	v_lshl_add_u64 v[234:235], s[10:11], 0, v[168:169]
	ds_read_b128 v[182:185], v212 offset:32768
	ds_read_b128 v[186:189], v212 offset:33792
	ds_read_b128 v[190:193], v212 offset:34816
	ds_read_b128 v[194:197], v212 offset:35840
	ds_read_b128 v[198:201], v212 offset:36864
	ds_read_b128 v[214:217], v212 offset:37888
	ds_read_b128 v[218:221], v212 offset:38912
	ds_read_b128 v[222:225], v212 offset:39936
	global_load_lds_dwordx4 v[234:235], off
	v_lshl_add_u64 v[234:235], s[10:11], 0, v[164:165]
	s_mov_b32 m0, s89
	s_nop 0
	global_load_lds_dwordx4 v[234:235], off
	s_waitcnt vmcnt(8) lgkmcnt(0)
	s_barrier
	s_setprio 1
	v_mfma_f32_16x16x32_bf16 v[6:9], v[122:125], v[182:185], v[6:9]
	v_mfma_f32_16x16x32_bf16 v[2:5], v[138:141], v[182:185], v[2:5]
	v_mfma_f32_16x16x32_bf16 v[134:137], v[122:125], v[190:193], v[134:137]
	v_mfma_f32_16x16x32_bf16 v[130:133], v[138:141], v[190:193], v[130:133]
	v_mfma_f32_16x16x32_bf16 v[118:121], v[122:125], v[198:201], v[118:121]
	v_mfma_f32_16x16x32_bf16 v[114:117], v[138:141], v[198:201], v[114:117]
	v_mfma_f32_16x16x32_bf16 v[110:113], v[122:125], v[218:221], v[110:113]
	v_mfma_f32_16x16x32_bf16 v[106:109], v[138:141], v[218:221], v[106:109]
	v_mfma_f32_16x16x32_bf16 v[6:9], v[126:129], v[186:189], v[6:9]
	v_mfma_f32_16x16x32_bf16 v[2:5], v[142:145], v[186:189], v[2:5]
	v_mfma_f32_16x16x32_bf16 v[134:137], v[126:129], v[194:197], v[134:137]
	v_mfma_f32_16x16x32_bf16 v[130:133], v[142:145], v[194:197], v[130:133]
	v_mfma_f32_16x16x32_bf16 v[118:121], v[126:129], v[214:217], v[118:121]
	v_mfma_f32_16x16x32_bf16 v[114:117], v[142:145], v[214:217], v[114:117]
	v_mfma_f32_16x16x32_bf16 v[110:113], v[126:129], v[222:225], v[110:113]
	v_mfma_f32_16x16x32_bf16 v[106:109], v[142:145], v[222:225], v[106:109]
	s_setprio 0
	s_setprio 1
	v_mfma_f32_16x16x32_bf16 v[70:73], v[146:149], v[182:185], v[70:73]
	v_mfma_f32_16x16x32_bf16 v[66:69], v[174:177], v[182:185], v[66:69]
	v_mfma_f32_16x16x32_bf16 v[62:65], v[146:149], v[190:193], v[62:65]
	v_mfma_f32_16x16x32_bf16 v[58:61], v[174:177], v[190:193], v[58:61]
	v_mfma_f32_16x16x32_bf16 v[54:57], v[146:149], v[198:201], v[54:57]
	v_mfma_f32_16x16x32_bf16 v[50:53], v[174:177], v[198:201], v[50:53]
	v_mfma_f32_16x16x32_bf16 v[46:49], v[146:149], v[218:221], v[46:49]
	v_mfma_f32_16x16x32_bf16 v[42:45], v[174:177], v[218:221], v[42:45]
	v_mfma_f32_16x16x32_bf16 v[70:73], v[150:153], v[186:189], v[70:73]
	v_mfma_f32_16x16x32_bf16 v[66:69], v[178:181], v[186:189], v[66:69]
	v_mfma_f32_16x16x32_bf16 v[62:65], v[150:153], v[194:197], v[62:65]
	v_mfma_f32_16x16x32_bf16 v[58:61], v[178:181], v[194:197], v[58:61]
	v_mfma_f32_16x16x32_bf16 v[54:57], v[150:153], v[214:217], v[54:57]
	v_mfma_f32_16x16x32_bf16 v[50:53], v[178:181], v[214:217], v[50:53]
	v_mfma_f32_16x16x32_bf16 v[46:49], v[150:153], v[222:225], v[46:49]
	v_mfma_f32_16x16x32_bf16 v[42:45], v[178:181], v[222:225], v[42:45]
	s_barrier
; #define PG8_STAGE(bufoff, gbase, voff) do { _Pragma("unroll") for (int _i = 0; _i < 2; ++_i) \
;         __builtin_amdgcn_global_load_lds((const unsigned*)((const char*)(gbase) + (voff)[_i]), (PG8_LAS unsigned*)(lds + (bufoff) + ldsw + _i * 8192), 16, 0, 0); } while (0)
; #define PG8_LDA(dst, b, h) do { _Pragma("unroll") for (int m = 0; m < 4; ++m) _Pragma("unroll") for (int k = 0; k < 2; ++k) dst[m][k] = *(const PG8_LAS bf16x8*)(lds + PG8_SA(b, h) + aoff + m * 2048 + k * 1024); } while (0)
; #define PG8_MMA(ai, bj, At, Bt) do { __builtin_amdgcn_s_setprio(1); _Pragma("unroll") for (int m = 0; m < 4; ++m) _Pragma("unroll") for (int n = 0; n < 2; ++n) _Pragma("unroll") for (int k = 0; k < 2; ++k) \
;         acc[ai][bj][m][n] = __builtin_amdgcn_mfma_f32_16x16x32_bf16(Bt[n][k], At[m][k], acc[ai][bj][m][n], 0, 0, 0); __builtin_amdgcn_s_setprio(0); } while (0)
; #define PG8_WAIT_V(n) asm volatile("s_waitcnt vmcnt(" #n ")" ::: "memory")
; #define PG8_WAIT_L(n) asm volatile("s_waitcnt lgkmcnt(" #n ")" ::: "memory")
; #define PG8_BAR __builtin_amdgcn_s_barrier()
; #define PG8_SCHED __builtin_amdgcn_sched_barrier(0)
; template <class Epi, class Sched, bool ALIGN_EPI = false, bool SP2 = false>
; __device__ __forceinline__ void gemm_phase(PG8_LAS unsigned char* lds, const Gemm g, const Sched& S, const Epi& E, const int wave_s) {
;     ...
;             PG8_LDA(At, 1, 1); PG8_STAGE(PG8_SB(1, 0), b3, voffB); PG8_STAGE(PG8_SB(1, 1), b3 + hstep, voffB); PG8_STAGE(PG8_SA(1, 0), a3, voffA);
;             PG8_WAIT_V(8); PG8_WAIT_L(0); PG8_BAR; PG8_MMA(1, 0, At, B0); PG8_MMA(1, 1, At, B1); PG8_BAR; PG8_SCHED;
;     ...
;         if constexpr (ALIGN_EPI) { if (wr == 0) PG8_BAR; }
	s_setprio 0
	s_add_i32 s10, s45, s44
	v_lshl_add_u64 v[226:227], v[226:227], 0, s[70:71]
	s_mov_b32 m0, s10
	ds_read_b128 v[182:185], v212 offset:49152
	ds_read_b128 v[186:189], v212 offset:50176
	ds_read_b128 v[190:193], v212 offset:51200
	ds_read_b128 v[194:197], v212 offset:52224
	ds_read_b128 v[198:201], v212 offset:53248
	ds_read_b128 v[214:217], v212 offset:54272
	ds_read_b128 v[218:221], v212 offset:55296
	ds_read_b128 v[222:225], v212 offset:56320
	global_load_lds_dwordx4 v[226:227], off
	s_add_i32 m0, s10, 0x2000
	s_add_u32 s10, s40, 0xb0080
	v_lshl_add_u64 v[226:227], v[228:229], 0, s[70:71]
	s_addc_u32 s11, s41, 0
	s_add_i32 s40, s80, s44
	global_load_lds_dwordx4 v[226:227], off
	v_lshl_add_u64 v[226:227], s[10:11], 0, v[166:167]
	s_mov_b32 m0, s40
	s_nop 0
	global_load_lds_dwordx4 v[226:227], off
	v_lshl_add_u64 v[226:227], s[10:11], 0, v[162:163]
	s_add_i32 m0, s40, 0x2000
	s_nop 0
	global_load_lds_dwordx4 v[226:227], off
	v_lshl_add_u64 v[226:227], v[230:231], 0, s[70:71]
	s_mov_b32 m0, s62
	s_nop 0
	global_load_lds_dwordx4 v[226:227], off
	v_lshl_add_u64 v[226:227], v[232:233], 0, s[70:71]
	s_mov_b32 m0, s68
	s_nop 0
	global_load_lds_dwordx4 v[226:227], off
	s_waitcnt vmcnt(8) lgkmcnt(0)
	s_barrier
	s_setprio 1
	v_mfma_f32_16x16x32_bf16 v[102:105], v[122:125], v[182:185], v[102:105]
	v_mfma_f32_16x16x32_bf16 v[98:101], v[138:141], v[182:185], v[98:101]
	v_mfma_f32_16x16x32_bf16 v[94:97], v[122:125], v[190:193], v[94:97]
	v_mfma_f32_16x16x32_bf16 v[90:93], v[138:141], v[190:193], v[90:93]
	v_mfma_f32_16x16x32_bf16 v[86:89], v[122:125], v[198:201], v[86:89]
	v_mfma_f32_16x16x32_bf16 v[82:85], v[138:141], v[198:201], v[82:85]
	v_mfma_f32_16x16x32_bf16 v[78:81], v[122:125], v[218:221], v[78:81]
	v_mfma_f32_16x16x32_bf16 v[74:77], v[138:141], v[218:221], v[74:77]
	v_mfma_f32_16x16x32_bf16 v[102:105], v[126:129], v[186:189], v[102:105]
	v_mfma_f32_16x16x32_bf16 v[98:101], v[142:145], v[186:189], v[98:101]
	v_mfma_f32_16x16x32_bf16 v[94:97], v[126:129], v[194:197], v[94:97]
	v_mfma_f32_16x16x32_bf16 v[90:93], v[142:145], v[194:197], v[90:93]
	v_mfma_f32_16x16x32_bf16 v[86:89], v[126:129], v[214:217], v[86:89]
	v_mfma_f32_16x16x32_bf16 v[82:85], v[142:145], v[214:217], v[82:85]
	v_mfma_f32_16x16x32_bf16 v[78:81], v[126:129], v[222:225], v[78:81]
	v_mfma_f32_16x16x32_bf16 v[74:77], v[142:145], v[222:225], v[74:77]
	s_setprio 0
	s_setprio 1
	v_mfma_f32_16x16x32_bf16 v[38:41], v[146:149], v[182:185], v[38:41]
	v_mfma_f32_16x16x32_bf16 v[34:37], v[174:177], v[182:185], v[34:37]
	v_mfma_f32_16x16x32_bf16 v[30:33], v[146:149], v[190:193], v[30:33]
	v_mfma_f32_16x16x32_bf16 v[26:29], v[174:177], v[190:193], v[26:29]
	v_mfma_f32_16x16x32_bf16 v[22:25], v[146:149], v[198:201], v[22:25]
	v_mfma_f32_16x16x32_bf16 v[18:21], v[174:177], v[198:201], v[18:21]
	v_mfma_f32_16x16x32_bf16 v[14:17], v[146:149], v[218:221], v[14:17]
	v_mfma_f32_16x16x32_bf16 v[10:13], v[174:177], v[218:221], v[10:13]
	v_mfma_f32_16x16x32_bf16 v[38:41], v[150:153], v[186:189], v[38:41]
	v_mfma_f32_16x16x32_bf16 v[34:37], v[178:181], v[186:189], v[34:37]
	v_mfma_f32_16x16x32_bf16 v[30:33], v[150:153], v[194:197], v[30:33]
	v_mfma_f32_16x16x32_bf16 v[26:29], v[178:181], v[194:197], v[26:29]
	v_mfma_f32_16x16x32_bf16 v[22:25], v[150:153], v[214:217], v[22:25]
	v_mfma_f32_16x16x32_bf16 v[18:21], v[178:181], v[214:217], v[18:21]
	v_mfma_f32_16x16x32_bf16 v[14:17], v[150:153], v[222:225], v[14:17]
	v_mfma_f32_16x16x32_bf16 v[10:13], v[178:181], v[222:225], v[10:13]
	s_barrier
	s_setprio 0
	s_add_i32 s75, s75, 2
	s_add_u32 vcc_lo, vcc_lo, 0x100
	s_addc_u32 vcc_hi, vcc_hi, 0
	s_cmp_gt_u32 s75, 41
	s_mov_b64 s[10:11], s[8:9]
	s_cbranch_scc0 .LBB0_806
	s_and_b64 vcc, exec, s[28:29]
	s_cbranch_vccz .LBB0_809
	s_barrier
